# all s_setprio removed from the six GEMM K-loops (equal priority for MFMA and loader waves), otherwise as the best version
# baseline (speedup 1.0000x reference)
.LBB0_306:
	ds_read_b128 v[166:169], v162
	ds_read_b128 v[170:173], v162 offset:1024
	ds_read_b128 v[174:177], v162 offset:2048
	ds_read_b128 v[180:183], v162 offset:3072
	ds_read_b128 v[184:187], v163
	ds_read_b128 v[188:191], v163 offset:1024
	ds_read_b128 v[192:195], v163 offset:2048
	ds_read_b128 v[196:199], v163 offset:3072
	s_add_u32 s30, s28, 0xfff80080
	s_addc_u32 s31, s29, -1
	s_cmp_eq_u32 s50, 28
	s_cselect_b32 s35, s3, s31
	s_cselect_b32 s34, s21, s30
	s_cselect_b32 s31, s19, s49
	s_cselect_b32 s30, s27, s48
	v_lshl_add_u64 v[160:161], s[28:29], 0, v[152:153]
	s_add_i32 m0, s33, 0xc000
	ds_read_b128 v[200:203], v164
	ds_read_b128 v[204:207], v164 offset:1024
	ds_read_b128 v[208:211], v164 offset:2048
	ds_read_b128 v[212:215], v164 offset:3072
	ds_read_b128 v[216:219], v164 offset:4096
	ds_read_b128 v[220:223], v164 offset:5120
	ds_read_b128 v[224:227], v164 offset:6144
	ds_read_b128 v[228:231], v164 offset:7168
	global_load_lds_dwordx4 v[160:161], off
	v_lshl_add_u64 v[160:161], s[28:29], 0, v[154:155]
	s_add_i32 m0, s33, 0xe000
	s_nop 0
	global_load_lds_dwordx4 v[160:161], off
	s_waitcnt vmcnt(8)
	s_waitcnt lgkmcnt(0)
	s_barrier
	v_mfma_f32_16x16x32_bf16 v[126:129], v[166:169], v[200:203], v[126:129]
	v_mfma_f32_16x16x32_bf16 v[122:125], v[174:177], v[200:203], v[122:125]
	v_mfma_f32_16x16x32_bf16 v[110:113], v[166:169], v[208:211], v[110:113]
	v_mfma_f32_16x16x32_bf16 v[106:109], v[174:177], v[208:211], v[106:109]
	v_mfma_f32_16x16x32_bf16 v[94:97], v[166:169], v[216:219], v[94:97]
	v_mfma_f32_16x16x32_bf16 v[90:93], v[174:177], v[216:219], v[90:93]
	v_mfma_f32_16x16x32_bf16 v[78:81], v[166:169], v[224:227], v[78:81]
	v_mfma_f32_16x16x32_bf16 v[74:77], v[174:177], v[224:227], v[74:77]
	v_mfma_f32_16x16x32_bf16 v[126:129], v[170:173], v[204:207], v[126:129]
	v_mfma_f32_16x16x32_bf16 v[122:125], v[180:183], v[204:207], v[122:125]
	v_mfma_f32_16x16x32_bf16 v[110:113], v[170:173], v[212:215], v[110:113]
	v_mfma_f32_16x16x32_bf16 v[106:109], v[180:183], v[212:215], v[106:109]
	v_mfma_f32_16x16x32_bf16 v[94:97], v[170:173], v[220:223], v[94:97]
	v_mfma_f32_16x16x32_bf16 v[90:93], v[180:183], v[220:223], v[90:93]
	v_mfma_f32_16x16x32_bf16 v[78:81], v[170:173], v[228:231], v[78:81]
	v_mfma_f32_16x16x32_bf16 v[74:77], v[180:183], v[228:231], v[74:77]
	v_mfma_f32_16x16x32_bf16 v[118:121], v[184:187], v[200:203], v[118:121]
	v_mfma_f32_16x16x32_bf16 v[114:117], v[192:195], v[200:203], v[114:117]
	v_mfma_f32_16x16x32_bf16 v[102:105], v[184:187], v[208:211], v[102:105]
	v_mfma_f32_16x16x32_bf16 v[98:101], v[192:195], v[208:211], v[98:101]
	v_mfma_f32_16x16x32_bf16 v[86:89], v[184:187], v[216:219], v[86:89]
	v_mfma_f32_16x16x32_bf16 v[82:85], v[192:195], v[216:219], v[82:85]
	v_mfma_f32_16x16x32_bf16 v[70:73], v[184:187], v[224:227], v[70:73]
	v_mfma_f32_16x16x32_bf16 v[66:69], v[192:195], v[224:227], v[66:69]
	v_mfma_f32_16x16x32_bf16 v[118:121], v[188:191], v[204:207], v[118:121]
	v_mfma_f32_16x16x32_bf16 v[114:117], v[196:199], v[204:207], v[114:117]
	v_mfma_f32_16x16x32_bf16 v[102:105], v[188:191], v[212:215], v[102:105]
	v_mfma_f32_16x16x32_bf16 v[98:101], v[196:199], v[212:215], v[98:101]
	v_mfma_f32_16x16x32_bf16 v[86:89], v[188:191], v[220:223], v[86:89]
	v_mfma_f32_16x16x32_bf16 v[82:85], v[196:199], v[220:223], v[82:85]
	v_mfma_f32_16x16x32_bf16 v[70:73], v[188:191], v[228:231], v[70:73]
	v_mfma_f32_16x16x32_bf16 v[66:69], v[196:199], v[228:231], v[66:69]
	s_barrier
	s_add_i32 s51, s45, s17
	v_lshl_add_u64 v[160:161], s[30:31], 0, v[138:139]
	s_mov_b32 m0, s51
	ds_read_b128 v[200:203], v164 offset:16384
	ds_read_b128 v[204:207], v164 offset:17408
	ds_read_b128 v[208:211], v164 offset:18432
	ds_read_b128 v[212:215], v164 offset:19456
	ds_read_b128 v[216:219], v164 offset:20480
	ds_read_b128 v[220:223], v164 offset:21504
	ds_read_b128 v[224:227], v164 offset:22528
	ds_read_b128 v[228:231], v164 offset:23552
	global_load_lds_dwordx4 v[160:161], off
	s_add_i32 m0, s51, 0x2000
	s_add_u32 s56, s30, 0x80000
	v_lshl_add_u64 v[232:233], s[30:31], 0, v[142:143]
	s_addc_u32 s57, s31, 0
	s_add_i32 s51, s47, s17
	global_load_lds_dwordx4 v[232:233], off
	v_lshl_add_u64 v[234:235], s[56:57], 0, v[138:139]
	s_mov_b32 m0, s51
	v_lshl_add_u64 v[236:237], s[34:35], 0, v[140:141]
	global_load_lds_dwordx4 v[234:235], off
	v_lshl_add_u64 v[234:235], s[56:57], 0, v[142:143]
	s_add_i32 m0, s51, 0x2000
	s_nop 0
	global_load_lds_dwordx4 v[234:235], off
	v_lshl_add_u64 v[234:235], s[34:35], 0, v[136:137]
	s_mov_b32 m0, s33
	s_nop 0
	global_load_lds_dwordx4 v[234:235], off
	s_mov_b32 m0, s36
	s_nop 0
	global_load_lds_dwordx4 v[236:237], off
	s_waitcnt vmcnt(8)
	s_waitcnt lgkmcnt(0)
	s_barrier
	v_mfma_f32_16x16x32_bf16 v[62:65], v[166:169], v[200:203], v[62:65]
	v_mfma_f32_16x16x32_bf16 v[58:61], v[174:177], v[200:203], v[58:61]
	v_mfma_f32_16x16x32_bf16 v[46:49], v[166:169], v[208:211], v[46:49]
	v_mfma_f32_16x16x32_bf16 v[42:45], v[174:177], v[208:211], v[42:45]
	v_mfma_f32_16x16x32_bf16 v[30:33], v[166:169], v[216:219], v[30:33]
	v_mfma_f32_16x16x32_bf16 v[26:29], v[174:177], v[216:219], v[26:29]
	v_mfma_f32_16x16x32_bf16 v[14:17], v[166:169], v[224:227], v[14:17]
	v_mfma_f32_16x16x32_bf16 v[10:13], v[174:177], v[224:227], v[10:13]
	v_mfma_f32_16x16x32_bf16 v[62:65], v[170:173], v[204:207], v[62:65]
	v_mfma_f32_16x16x32_bf16 v[58:61], v[180:183], v[204:207], v[58:61]
	v_mfma_f32_16x16x32_bf16 v[46:49], v[170:173], v[212:215], v[46:49]
	v_mfma_f32_16x16x32_bf16 v[42:45], v[180:183], v[212:215], v[42:45]
	v_mfma_f32_16x16x32_bf16 v[30:33], v[170:173], v[220:223], v[30:33]
	v_mfma_f32_16x16x32_bf16 v[26:29], v[180:183], v[220:223], v[26:29]
	v_mfma_f32_16x16x32_bf16 v[14:17], v[170:173], v[228:231], v[14:17]
	v_mfma_f32_16x16x32_bf16 v[10:13], v[180:183], v[228:231], v[10:13]
	v_mfma_f32_16x16x32_bf16 v[54:57], v[184:187], v[200:203], v[54:57]
	v_mfma_f32_16x16x32_bf16 v[50:53], v[192:195], v[200:203], v[50:53]
	v_mfma_f32_16x16x32_bf16 v[38:41], v[184:187], v[208:211], v[38:41]
	v_mfma_f32_16x16x32_bf16 v[34:37], v[192:195], v[208:211], v[34:37]
	v_mfma_f32_16x16x32_bf16 v[22:25], v[184:187], v[216:219], v[22:25]
	v_mfma_f32_16x16x32_bf16 v[18:21], v[192:195], v[216:219], v[18:21]
	v_mfma_f32_16x16x32_bf16 v[6:9], v[184:187], v[224:227], v[6:9]
	v_mfma_f32_16x16x32_bf16 v[2:5], v[192:195], v[224:227], v[2:5]
	v_mfma_f32_16x16x32_bf16 v[54:57], v[188:191], v[204:207], v[54:57]
	v_mfma_f32_16x16x32_bf16 v[50:53], v[196:199], v[204:207], v[50:53]
	v_mfma_f32_16x16x32_bf16 v[38:41], v[188:191], v[212:215], v[38:41]
	v_mfma_f32_16x16x32_bf16 v[34:37], v[196:199], v[212:215], v[34:37]
	v_mfma_f32_16x16x32_bf16 v[22:25], v[188:191], v[220:223], v[22:25]
	v_mfma_f32_16x16x32_bf16 v[18:21], v[196:199], v[220:223], v[18:21]
	v_mfma_f32_16x16x32_bf16 v[6:9], v[188:191], v[228:231], v[6:9]
	v_mfma_f32_16x16x32_bf16 v[2:5], v[196:199], v[228:231], v[2:5]
	s_barrier
	s_add_i32 s51, 0, 0x18000
	v_add_u32_e32 v144, s51, v135
	s_add_i32 s56, 0, 0x1c000
	ds_read_b128 v[166:169], v144
	ds_read_b128 v[170:173], v144 offset:1024
	ds_read_b128 v[174:177], v144 offset:2048
	ds_read_b128 v[180:183], v144 offset:3072
	v_add_u32_e32 v144, s56, v135
	ds_read_b128 v[184:187], v144
	ds_read_b128 v[188:191], v144 offset:1024
	ds_read_b128 v[192:195], v144 offset:2048
	ds_read_b128 v[196:199], v144 offset:3072
	s_add_u32 s34, s34, 0x80000
	s_addc_u32 s35, s35, 0
	s_mov_b32 m0, s37
	v_lshl_add_u64 v[238:239], s[34:35], 0, v[136:137]
	ds_read_b128 v[200:203], v164 offset:32768
	ds_read_b128 v[204:207], v164 offset:33792
	ds_read_b128 v[208:211], v164 offset:34816
	ds_read_b128 v[212:215], v164 offset:35840
	ds_read_b128 v[216:219], v164 offset:36864
	ds_read_b128 v[220:223], v164 offset:37888
	ds_read_b128 v[224:227], v164 offset:38912
	ds_read_b128 v[228:231], v164 offset:39936
	global_load_lds_dwordx4 v[238:239], off
	v_lshl_add_u64 v[238:239], s[34:35], 0, v[140:141]
	s_mov_b32 m0, s38
	s_nop 0
	global_load_lds_dwordx4 v[238:239], off
	s_waitcnt vmcnt(8)
	s_waitcnt lgkmcnt(0)
	s_barrier
	v_mfma_f32_16x16x32_bf16 v[126:129], v[166:169], v[200:203], v[126:129]
	v_mfma_f32_16x16x32_bf16 v[122:125], v[174:177], v[200:203], v[122:125]
	v_mfma_f32_16x16x32_bf16 v[110:113], v[166:169], v[208:211], v[110:113]
	v_mfma_f32_16x16x32_bf16 v[106:109], v[174:177], v[208:211], v[106:109]
	v_mfma_f32_16x16x32_bf16 v[94:97], v[166:169], v[216:219], v[94:97]
	v_mfma_f32_16x16x32_bf16 v[90:93], v[174:177], v[216:219], v[90:93]
	v_mfma_f32_16x16x32_bf16 v[78:81], v[166:169], v[224:227], v[78:81]
	v_mfma_f32_16x16x32_bf16 v[74:77], v[174:177], v[224:227], v[74:77]
	v_mfma_f32_16x16x32_bf16 v[126:129], v[170:173], v[204:207], v[126:129]
	v_mfma_f32_16x16x32_bf16 v[122:125], v[180:183], v[204:207], v[122:125]
	v_mfma_f32_16x16x32_bf16 v[110:113], v[170:173], v[212:215], v[110:113]
	v_mfma_f32_16x16x32_bf16 v[106:109], v[180:183], v[212:215], v[106:109]
	v_mfma_f32_16x16x32_bf16 v[94:97], v[170:173], v[220:223], v[94:97]
	v_mfma_f32_16x16x32_bf16 v[90:93], v[180:183], v[220:223], v[90:93]
	v_mfma_f32_16x16x32_bf16 v[78:81], v[170:173], v[228:231], v[78:81]
	v_mfma_f32_16x16x32_bf16 v[74:77], v[180:183], v[228:231], v[74:77]
	v_mfma_f32_16x16x32_bf16 v[118:121], v[184:187], v[200:203], v[118:121]
	v_mfma_f32_16x16x32_bf16 v[114:117], v[192:195], v[200:203], v[114:117]
	v_mfma_f32_16x16x32_bf16 v[102:105], v[184:187], v[208:211], v[102:105]
	v_mfma_f32_16x16x32_bf16 v[98:101], v[192:195], v[208:211], v[98:101]
	v_mfma_f32_16x16x32_bf16 v[86:89], v[184:187], v[216:219], v[86:89]
	v_mfma_f32_16x16x32_bf16 v[82:85], v[192:195], v[216:219], v[82:85]
	v_mfma_f32_16x16x32_bf16 v[70:73], v[184:187], v[224:227], v[70:73]
	v_mfma_f32_16x16x32_bf16 v[66:69], v[192:195], v[224:227], v[66:69]
	v_mfma_f32_16x16x32_bf16 v[118:121], v[188:191], v[204:207], v[118:121]
	v_mfma_f32_16x16x32_bf16 v[114:117], v[196:199], v[204:207], v[114:117]
	v_mfma_f32_16x16x32_bf16 v[102:105], v[188:191], v[212:215], v[102:105]
	v_mfma_f32_16x16x32_bf16 v[98:101], v[196:199], v[212:215], v[98:101]
	v_mfma_f32_16x16x32_bf16 v[86:89], v[188:191], v[220:223], v[86:89]
	v_mfma_f32_16x16x32_bf16 v[82:85], v[196:199], v[220:223], v[82:85]
	v_mfma_f32_16x16x32_bf16 v[70:73], v[188:191], v[228:231], v[70:73]
	v_mfma_f32_16x16x32_bf16 v[66:69], v[196:199], v[228:231], v[66:69]
	s_barrier
	s_add_i32 s34, s51, s17
	v_lshl_add_u64 v[160:161], v[160:161], 0, s[6:7]
	s_mov_b32 m0, s34
	ds_read_b128 v[200:203], v164 offset:49152
	ds_read_b128 v[204:207], v164 offset:50176
	ds_read_b128 v[208:211], v164 offset:51200
	ds_read_b128 v[212:215], v164 offset:52224
	ds_read_b128 v[216:219], v164 offset:53248
	ds_read_b128 v[220:223], v164 offset:54272
	ds_read_b128 v[224:227], v164 offset:55296
	ds_read_b128 v[228:231], v164 offset:56320
	global_load_lds_dwordx4 v[160:161], off
	s_add_i32 m0, s34, 0x2000
	s_add_u32 s30, s30, 0x80080
	v_lshl_add_u64 v[160:161], v[232:233], 0, s[6:7]
	s_addc_u32 s31, s31, 0
	s_add_i32 s34, s56, s17
	global_load_lds_dwordx4 v[160:161], off
	v_lshl_add_u64 v[160:161], s[30:31], 0, v[138:139]
	s_mov_b32 m0, s34
	s_nop 0
	global_load_lds_dwordx4 v[160:161], off
	v_lshl_add_u64 v[160:161], s[30:31], 0, v[142:143]
	s_add_i32 m0, s34, 0x2000
	s_nop 0
	global_load_lds_dwordx4 v[160:161], off
	v_lshl_add_u64 v[160:161], v[234:235], 0, s[6:7]
	s_mov_b32 m0, s40
	s_nop 0
	global_load_lds_dwordx4 v[160:161], off
	v_lshl_add_u64 v[160:161], v[236:237], 0, s[6:7]
	s_mov_b32 m0, s41
	s_nop 0
	global_load_lds_dwordx4 v[160:161], off
	s_waitcnt vmcnt(8)
	s_waitcnt lgkmcnt(0)
	s_barrier
	v_mfma_f32_16x16x32_bf16 v[62:65], v[166:169], v[200:203], v[62:65]
	v_mfma_f32_16x16x32_bf16 v[58:61], v[174:177], v[200:203], v[58:61]
	v_mfma_f32_16x16x32_bf16 v[46:49], v[166:169], v[208:211], v[46:49]
	v_mfma_f32_16x16x32_bf16 v[42:45], v[174:177], v[208:211], v[42:45]
	v_mfma_f32_16x16x32_bf16 v[30:33], v[166:169], v[216:219], v[30:33]
	v_mfma_f32_16x16x32_bf16 v[26:29], v[174:177], v[216:219], v[26:29]
	v_mfma_f32_16x16x32_bf16 v[14:17], v[166:169], v[224:227], v[14:17]
	v_mfma_f32_16x16x32_bf16 v[10:13], v[174:177], v[224:227], v[10:13]
	v_mfma_f32_16x16x32_bf16 v[62:65], v[170:173], v[204:207], v[62:65]
	v_mfma_f32_16x16x32_bf16 v[58:61], v[180:183], v[204:207], v[58:61]
	v_mfma_f32_16x16x32_bf16 v[46:49], v[170:173], v[212:215], v[46:49]
	v_mfma_f32_16x16x32_bf16 v[42:45], v[180:183], v[212:215], v[42:45]
	v_mfma_f32_16x16x32_bf16 v[30:33], v[170:173], v[220:223], v[30:33]
	v_mfma_f32_16x16x32_bf16 v[26:29], v[180:183], v[220:223], v[26:29]
	v_mfma_f32_16x16x32_bf16 v[14:17], v[170:173], v[228:231], v[14:17]
	v_mfma_f32_16x16x32_bf16 v[10:13], v[180:183], v[228:231], v[10:13]
	v_mfma_f32_16x16x32_bf16 v[54:57], v[184:187], v[200:203], v[54:57]
	v_mfma_f32_16x16x32_bf16 v[50:53], v[192:195], v[200:203], v[50:53]
	v_mfma_f32_16x16x32_bf16 v[38:41], v[184:187], v[208:211], v[38:41]
	v_mfma_f32_16x16x32_bf16 v[34:37], v[192:195], v[208:211], v[34:37]
	v_mfma_f32_16x16x32_bf16 v[22:25], v[184:187], v[216:219], v[22:25]
	v_mfma_f32_16x16x32_bf16 v[18:21], v[192:195], v[216:219], v[18:21]
	v_mfma_f32_16x16x32_bf16 v[6:9], v[184:187], v[224:227], v[6:9]
	v_mfma_f32_16x16x32_bf16 v[2:5], v[192:195], v[224:227], v[2:5]
	v_mfma_f32_16x16x32_bf16 v[54:57], v[188:191], v[204:207], v[54:57]
	v_mfma_f32_16x16x32_bf16 v[50:53], v[196:199], v[204:207], v[50:53]
	v_mfma_f32_16x16x32_bf16 v[38:41], v[188:191], v[212:215], v[38:41]
	v_mfma_f32_16x16x32_bf16 v[34:37], v[196:199], v[212:215], v[34:37]
	v_mfma_f32_16x16x32_bf16 v[22:25], v[188:191], v[220:223], v[22:25]
	v_mfma_f32_16x16x32_bf16 v[18:21], v[196:199], v[220:223], v[18:21]
	v_mfma_f32_16x16x32_bf16 v[6:9], v[188:191], v[228:231], v[6:9]
	v_mfma_f32_16x16x32_bf16 v[2:5], v[196:199], v[228:231], v[2:5]
	s_barrier
	s_add_i32 s50, s50, 2
	s_add_u32 s28, s28, 0x100
	s_addc_u32 s29, s29, 0
	s_add_u32 s48, s48, 0x100
	s_addc_u32 s49, s49, 0
	s_cmp_gt_u32 s50, 29
	s_cbranch_scc0 .LBB0_306
	s_and_b64 vcc, exec, s[8:9]
	s_cbranch_vccz .LBB0_314
	s_barrier
	v_lshl_add_u32 v160, s26, 8, v133
	s_cmp_gt_i32 s2, 35
	s_mov_b64 s[26:27], -1
	s_cbranch_scc1 .LBB0_315

.LBB0_986:
	ds_read_b128 v[148:151], v155
	ds_read_b128 v[158:161], v155 offset:1024
	ds_read_b128 v[162:165], v155 offset:2048
	ds_read_b128 v[166:169], v155 offset:3072
	ds_read_b128 v[170:173], v156
	ds_read_b128 v[174:177], v156 offset:1024
	ds_read_b128 v[180:183], v156 offset:2048
	ds_read_b128 v[184:187], v156 offset:3072
	s_add_u32 s26, s24, 0xfffc0080
	s_addc_u32 s27, s25, -1
	s_cmp_eq_u32 s49, 12
	s_cselect_b32 s29, s17, s27
	s_cselect_b32 s28, s45, s26
	s_cselect_b32 s27, s15, s48
	s_cselect_b32 s26, s46, s47
	v_lshl_add_u64 v[220:221], s[24:25], 0, v[138:139]
	s_add_i32 m0, s23, 0xc000
	ds_read_b128 v[188:191], v157
	ds_read_b128 v[192:195], v157 offset:1024
	ds_read_b128 v[196:199], v157 offset:2048
	ds_read_b128 v[200:203], v157 offset:3072
	ds_read_b128 v[204:207], v157 offset:4096
	ds_read_b128 v[208:211], v157 offset:5120
	ds_read_b128 v[212:215], v157 offset:6144
	ds_read_b128 v[216:219], v157 offset:7168
	global_load_lds_dwordx4 v[220:221], off
	v_lshl_add_u64 v[220:221], s[24:25], 0, v[140:141]
	s_add_i32 m0, s23, 0xe000
	s_nop 0
	global_load_lds_dwordx4 v[220:221], off
	s_waitcnt vmcnt(8)
	s_waitcnt lgkmcnt(0)
	s_barrier
	v_mfma_f32_16x16x32_bf16 v[126:129], v[148:151], v[188:191], v[126:129]
	v_mfma_f32_16x16x32_bf16 v[122:125], v[162:165], v[188:191], v[122:125]
	v_mfma_f32_16x16x32_bf16 v[110:113], v[148:151], v[196:199], v[110:113]
	v_mfma_f32_16x16x32_bf16 v[106:109], v[162:165], v[196:199], v[106:109]
	v_mfma_f32_16x16x32_bf16 v[94:97], v[148:151], v[204:207], v[94:97]
	v_mfma_f32_16x16x32_bf16 v[90:93], v[162:165], v[204:207], v[90:93]
	v_mfma_f32_16x16x32_bf16 v[78:81], v[148:151], v[212:215], v[78:81]
	v_mfma_f32_16x16x32_bf16 v[74:77], v[162:165], v[212:215], v[74:77]
	v_mfma_f32_16x16x32_bf16 v[126:129], v[158:161], v[192:195], v[126:129]
	v_mfma_f32_16x16x32_bf16 v[122:125], v[166:169], v[192:195], v[122:125]
	v_mfma_f32_16x16x32_bf16 v[110:113], v[158:161], v[200:203], v[110:113]
	v_mfma_f32_16x16x32_bf16 v[106:109], v[166:169], v[200:203], v[106:109]
	v_mfma_f32_16x16x32_bf16 v[94:97], v[158:161], v[208:211], v[94:97]
	v_mfma_f32_16x16x32_bf16 v[90:93], v[166:169], v[208:211], v[90:93]
	v_mfma_f32_16x16x32_bf16 v[78:81], v[158:161], v[216:219], v[78:81]
	v_mfma_f32_16x16x32_bf16 v[74:77], v[166:169], v[216:219], v[74:77]
	v_mfma_f32_16x16x32_bf16 v[118:121], v[170:173], v[188:191], v[118:121]
	v_mfma_f32_16x16x32_bf16 v[114:117], v[180:183], v[188:191], v[114:117]
	v_mfma_f32_16x16x32_bf16 v[102:105], v[170:173], v[196:199], v[102:105]
	v_mfma_f32_16x16x32_bf16 v[98:101], v[180:183], v[196:199], v[98:101]
	v_mfma_f32_16x16x32_bf16 v[86:89], v[170:173], v[204:207], v[86:89]
	v_mfma_f32_16x16x32_bf16 v[82:85], v[180:183], v[204:207], v[82:85]
	v_mfma_f32_16x16x32_bf16 v[70:73], v[170:173], v[212:215], v[70:73]
	v_mfma_f32_16x16x32_bf16 v[66:69], v[180:183], v[212:215], v[66:69]
	v_mfma_f32_16x16x32_bf16 v[118:121], v[174:177], v[192:195], v[118:121]
	v_mfma_f32_16x16x32_bf16 v[114:117], v[184:187], v[192:195], v[114:117]
	v_mfma_f32_16x16x32_bf16 v[102:105], v[174:177], v[200:203], v[102:105]
	v_mfma_f32_16x16x32_bf16 v[98:101], v[184:187], v[200:203], v[98:101]
	v_mfma_f32_16x16x32_bf16 v[86:89], v[174:177], v[208:211], v[86:89]
	v_mfma_f32_16x16x32_bf16 v[82:85], v[184:187], v[208:211], v[82:85]
	v_mfma_f32_16x16x32_bf16 v[70:73], v[174:177], v[216:219], v[70:73]
	v_mfma_f32_16x16x32_bf16 v[66:69], v[184:187], v[216:219], v[66:69]
	s_barrier
	s_add_i32 s50, s42, s30
	v_lshl_add_u64 v[220:221], s[26:27], 0, v[134:135]
	s_mov_b32 m0, s50
	ds_read_b128 v[188:191], v157 offset:16384
	ds_read_b128 v[192:195], v157 offset:17408
	ds_read_b128 v[196:199], v157 offset:18432
	ds_read_b128 v[200:203], v157 offset:19456
	ds_read_b128 v[204:207], v157 offset:20480
	ds_read_b128 v[208:211], v157 offset:21504
	ds_read_b128 v[212:215], v157 offset:22528
	ds_read_b128 v[216:219], v157 offset:23552
	global_load_lds_dwordx4 v[220:221], off
	s_add_i32 m0, s50, 0x2000
	s_add_u32 s50, s26, 0x40000
	v_lshl_add_u64 v[222:223], s[26:27], 0, v[130:131]
	s_addc_u32 s51, s27, 0
	s_add_i32 s56, s43, s30
	global_load_lds_dwordx4 v[222:223], off
	v_lshl_add_u64 v[224:225], s[50:51], 0, v[134:135]
	s_mov_b32 m0, s56
	v_lshl_add_u64 v[226:227], s[28:29], 0, v[132:133]
	global_load_lds_dwordx4 v[224:225], off
	v_lshl_add_u64 v[224:225], s[50:51], 0, v[130:131]
	s_add_i32 m0, s56, 0x2000
	s_nop 0
	global_load_lds_dwordx4 v[224:225], off
	v_lshl_add_u64 v[224:225], s[28:29], 0, v[136:137]
	s_mov_b32 m0, s23
	s_nop 0
	global_load_lds_dwordx4 v[224:225], off
	s_mov_b32 m0, s34
	s_nop 0
	global_load_lds_dwordx4 v[226:227], off
	s_waitcnt vmcnt(8)
	s_waitcnt lgkmcnt(0)
	s_barrier
	v_mfma_f32_16x16x32_bf16 v[62:65], v[148:151], v[188:191], v[62:65]
	v_mfma_f32_16x16x32_bf16 v[58:61], v[162:165], v[188:191], v[58:61]
	v_mfma_f32_16x16x32_bf16 v[46:49], v[148:151], v[196:199], v[46:49]
	v_mfma_f32_16x16x32_bf16 v[42:45], v[162:165], v[196:199], v[42:45]
	v_mfma_f32_16x16x32_bf16 v[30:33], v[148:151], v[204:207], v[30:33]
	v_mfma_f32_16x16x32_bf16 v[26:29], v[162:165], v[204:207], v[26:29]
	v_mfma_f32_16x16x32_bf16 v[14:17], v[148:151], v[212:215], v[14:17]
	v_mfma_f32_16x16x32_bf16 v[10:13], v[162:165], v[212:215], v[10:13]
	v_mfma_f32_16x16x32_bf16 v[62:65], v[158:161], v[192:195], v[62:65]
	v_mfma_f32_16x16x32_bf16 v[58:61], v[166:169], v[192:195], v[58:61]
	v_mfma_f32_16x16x32_bf16 v[46:49], v[158:161], v[200:203], v[46:49]
	v_mfma_f32_16x16x32_bf16 v[42:45], v[166:169], v[200:203], v[42:45]
	v_mfma_f32_16x16x32_bf16 v[30:33], v[158:161], v[208:211], v[30:33]
	v_mfma_f32_16x16x32_bf16 v[26:29], v[166:169], v[208:211], v[26:29]
	v_mfma_f32_16x16x32_bf16 v[14:17], v[158:161], v[216:219], v[14:17]
	v_mfma_f32_16x16x32_bf16 v[10:13], v[166:169], v[216:219], v[10:13]
	v_mfma_f32_16x16x32_bf16 v[54:57], v[170:173], v[188:191], v[54:57]
	v_mfma_f32_16x16x32_bf16 v[50:53], v[180:183], v[188:191], v[50:53]
	v_mfma_f32_16x16x32_bf16 v[38:41], v[170:173], v[196:199], v[38:41]
	v_mfma_f32_16x16x32_bf16 v[34:37], v[180:183], v[196:199], v[34:37]
	v_mfma_f32_16x16x32_bf16 v[22:25], v[170:173], v[204:207], v[22:25]
	v_mfma_f32_16x16x32_bf16 v[18:21], v[180:183], v[204:207], v[18:21]
	v_mfma_f32_16x16x32_bf16 v[6:9], v[170:173], v[212:215], v[6:9]
	v_mfma_f32_16x16x32_bf16 v[2:5], v[180:183], v[212:215], v[2:5]
	v_mfma_f32_16x16x32_bf16 v[54:57], v[174:177], v[192:195], v[54:57]
	v_mfma_f32_16x16x32_bf16 v[50:53], v[184:187], v[192:195], v[50:53]
	v_mfma_f32_16x16x32_bf16 v[38:41], v[174:177], v[200:203], v[38:41]
	v_mfma_f32_16x16x32_bf16 v[34:37], v[184:187], v[200:203], v[34:37]
	v_mfma_f32_16x16x32_bf16 v[22:25], v[174:177], v[208:211], v[22:25]
	v_mfma_f32_16x16x32_bf16 v[18:21], v[184:187], v[208:211], v[18:21]
	v_mfma_f32_16x16x32_bf16 v[6:9], v[174:177], v[216:219], v[6:9]
	v_mfma_f32_16x16x32_bf16 v[2:5], v[184:187], v[216:219], v[2:5]
	s_barrier
	s_add_i32 s50, 0, 0x18000
	s_add_i32 s51, 0, 0x1c000
	v_add_u32_e32 v166, s50, v153
	v_add_u32_e32 v179, s51, v153
	ds_read_b128 v[148:151], v166
	ds_read_b128 v[158:161], v166 offset:1024
	ds_read_b128 v[162:165], v166 offset:2048
	ds_read_b128 v[166:169], v166 offset:3072
	ds_read_b128 v[170:173], v179
	ds_read_b128 v[174:177], v179 offset:1024
	ds_read_b128 v[180:183], v179 offset:2048
	ds_read_b128 v[184:187], v179 offset:3072
	s_add_u32 s28, s28, 0x40000
	s_addc_u32 s29, s29, 0
	s_mov_b32 m0, s35
	v_lshl_add_u64 v[228:229], s[28:29], 0, v[136:137]
	ds_read_b128 v[188:191], v157 offset:32768
	ds_read_b128 v[192:195], v157 offset:33792
	ds_read_b128 v[196:199], v157 offset:34816
	ds_read_b128 v[200:203], v157 offset:35840
	ds_read_b128 v[204:207], v157 offset:36864
	ds_read_b128 v[208:211], v157 offset:37888
	ds_read_b128 v[212:215], v157 offset:38912
	ds_read_b128 v[216:219], v157 offset:39936
	global_load_lds_dwordx4 v[228:229], off
	v_lshl_add_u64 v[228:229], s[28:29], 0, v[132:133]
	s_mov_b32 m0, s36
	s_nop 0
	global_load_lds_dwordx4 v[228:229], off
	s_waitcnt vmcnt(8)
	s_waitcnt lgkmcnt(0)
	s_barrier
	v_mfma_f32_16x16x32_bf16 v[126:129], v[148:151], v[188:191], v[126:129]
	v_mfma_f32_16x16x32_bf16 v[122:125], v[162:165], v[188:191], v[122:125]
	v_mfma_f32_16x16x32_bf16 v[110:113], v[148:151], v[196:199], v[110:113]
	v_mfma_f32_16x16x32_bf16 v[106:109], v[162:165], v[196:199], v[106:109]
	v_mfma_f32_16x16x32_bf16 v[94:97], v[148:151], v[204:207], v[94:97]
	v_mfma_f32_16x16x32_bf16 v[90:93], v[162:165], v[204:207], v[90:93]
	v_mfma_f32_16x16x32_bf16 v[78:81], v[148:151], v[212:215], v[78:81]
	v_mfma_f32_16x16x32_bf16 v[74:77], v[162:165], v[212:215], v[74:77]
	v_mfma_f32_16x16x32_bf16 v[126:129], v[158:161], v[192:195], v[126:129]
	v_mfma_f32_16x16x32_bf16 v[122:125], v[166:169], v[192:195], v[122:125]
	v_mfma_f32_16x16x32_bf16 v[110:113], v[158:161], v[200:203], v[110:113]
	v_mfma_f32_16x16x32_bf16 v[106:109], v[166:169], v[200:203], v[106:109]
	v_mfma_f32_16x16x32_bf16 v[94:97], v[158:161], v[208:211], v[94:97]
	v_mfma_f32_16x16x32_bf16 v[90:93], v[166:169], v[208:211], v[90:93]
	v_mfma_f32_16x16x32_bf16 v[78:81], v[158:161], v[216:219], v[78:81]
	v_mfma_f32_16x16x32_bf16 v[74:77], v[166:169], v[216:219], v[74:77]
	v_mfma_f32_16x16x32_bf16 v[118:121], v[170:173], v[188:191], v[118:121]
	v_mfma_f32_16x16x32_bf16 v[114:117], v[180:183], v[188:191], v[114:117]
	v_mfma_f32_16x16x32_bf16 v[102:105], v[170:173], v[196:199], v[102:105]
	v_mfma_f32_16x16x32_bf16 v[98:101], v[180:183], v[196:199], v[98:101]
	v_mfma_f32_16x16x32_bf16 v[86:89], v[170:173], v[204:207], v[86:89]
	v_mfma_f32_16x16x32_bf16 v[82:85], v[180:183], v[204:207], v[82:85]
	v_mfma_f32_16x16x32_bf16 v[70:73], v[170:173], v[212:215], v[70:73]
	v_mfma_f32_16x16x32_bf16 v[66:69], v[180:183], v[212:215], v[66:69]
	v_mfma_f32_16x16x32_bf16 v[118:121], v[174:177], v[192:195], v[118:121]
	v_mfma_f32_16x16x32_bf16 v[114:117], v[184:187], v[192:195], v[114:117]
	v_mfma_f32_16x16x32_bf16 v[102:105], v[174:177], v[200:203], v[102:105]
	v_mfma_f32_16x16x32_bf16 v[98:101], v[184:187], v[200:203], v[98:101]
	v_mfma_f32_16x16x32_bf16 v[86:89], v[174:177], v[208:211], v[86:89]
	v_mfma_f32_16x16x32_bf16 v[82:85], v[184:187], v[208:211], v[82:85]
	v_mfma_f32_16x16x32_bf16 v[70:73], v[174:177], v[216:219], v[70:73]
	v_mfma_f32_16x16x32_bf16 v[66:69], v[184:187], v[216:219], v[66:69]
	s_barrier
	s_add_i32 s28, s50, s30
	v_lshl_add_u64 v[220:221], v[220:221], 0, s[4:5]
	s_mov_b32 m0, s28
	ds_read_b128 v[188:191], v157 offset:49152
	ds_read_b128 v[192:195], v157 offset:50176
	ds_read_b128 v[196:199], v157 offset:51200
	ds_read_b128 v[200:203], v157 offset:52224
	ds_read_b128 v[204:207], v157 offset:53248
	ds_read_b128 v[208:211], v157 offset:54272
	ds_read_b128 v[212:215], v157 offset:55296
	ds_read_b128 v[216:219], v157 offset:56320
	global_load_lds_dwordx4 v[220:221], off
	s_add_i32 m0, s28, 0x2000
	s_add_u32 s26, s26, 0x40080
	v_lshl_add_u64 v[220:221], v[222:223], 0, s[4:5]
	s_addc_u32 s27, s27, 0
	s_add_i32 s28, s51, s30
	global_load_lds_dwordx4 v[220:221], off
	v_lshl_add_u64 v[220:221], s[26:27], 0, v[134:135]
	s_mov_b32 m0, s28
	s_nop 0
	global_load_lds_dwordx4 v[220:221], off
	v_lshl_add_u64 v[220:221], s[26:27], 0, v[130:131]
	s_add_i32 m0, s28, 0x2000
	s_nop 0
	global_load_lds_dwordx4 v[220:221], off
	v_lshl_add_u64 v[220:221], v[224:225], 0, s[4:5]
	s_mov_b32 m0, s38
	s_nop 0
	global_load_lds_dwordx4 v[220:221], off
	v_lshl_add_u64 v[220:221], v[226:227], 0, s[4:5]
	s_mov_b32 m0, s39
	s_nop 0
	global_load_lds_dwordx4 v[220:221], off
	s_waitcnt vmcnt(8)
	s_waitcnt lgkmcnt(0)
	s_barrier
	v_mfma_f32_16x16x32_bf16 v[62:65], v[148:151], v[188:191], v[62:65]
	v_mfma_f32_16x16x32_bf16 v[58:61], v[162:165], v[188:191], v[58:61]
	v_mfma_f32_16x16x32_bf16 v[46:49], v[148:151], v[196:199], v[46:49]
	v_mfma_f32_16x16x32_bf16 v[42:45], v[162:165], v[196:199], v[42:45]
	v_mfma_f32_16x16x32_bf16 v[30:33], v[148:151], v[204:207], v[30:33]
	v_mfma_f32_16x16x32_bf16 v[26:29], v[162:165], v[204:207], v[26:29]
	v_mfma_f32_16x16x32_bf16 v[14:17], v[148:151], v[212:215], v[14:17]
	v_mfma_f32_16x16x32_bf16 v[10:13], v[162:165], v[212:215], v[10:13]
	v_mfma_f32_16x16x32_bf16 v[62:65], v[158:161], v[192:195], v[62:65]
	v_mfma_f32_16x16x32_bf16 v[58:61], v[166:169], v[192:195], v[58:61]
	v_mfma_f32_16x16x32_bf16 v[46:49], v[158:161], v[200:203], v[46:49]
	v_mfma_f32_16x16x32_bf16 v[42:45], v[166:169], v[200:203], v[42:45]
	v_mfma_f32_16x16x32_bf16 v[30:33], v[158:161], v[208:211], v[30:33]
	v_mfma_f32_16x16x32_bf16 v[26:29], v[166:169], v[208:211], v[26:29]
	v_mfma_f32_16x16x32_bf16 v[14:17], v[158:161], v[216:219], v[14:17]
	v_mfma_f32_16x16x32_bf16 v[10:13], v[166:169], v[216:219], v[10:13]
	v_mfma_f32_16x16x32_bf16 v[54:57], v[170:173], v[188:191], v[54:57]
	v_mfma_f32_16x16x32_bf16 v[50:53], v[180:183], v[188:191], v[50:53]
	v_mfma_f32_16x16x32_bf16 v[38:41], v[170:173], v[196:199], v[38:41]
	v_mfma_f32_16x16x32_bf16 v[34:37], v[180:183], v[196:199], v[34:37]
	v_mfma_f32_16x16x32_bf16 v[22:25], v[170:173], v[204:207], v[22:25]
	v_mfma_f32_16x16x32_bf16 v[18:21], v[180:183], v[204:207], v[18:21]
	v_mfma_f32_16x16x32_bf16 v[6:9], v[170:173], v[212:215], v[6:9]
	v_mfma_f32_16x16x32_bf16 v[2:5], v[180:183], v[212:215], v[2:5]
	v_mfma_f32_16x16x32_bf16 v[54:57], v[174:177], v[192:195], v[54:57]
	v_mfma_f32_16x16x32_bf16 v[50:53], v[184:187], v[192:195], v[50:53]
	v_mfma_f32_16x16x32_bf16 v[38:41], v[174:177], v[200:203], v[38:41]
	v_mfma_f32_16x16x32_bf16 v[34:37], v[184:187], v[200:203], v[34:37]
	v_mfma_f32_16x16x32_bf16 v[22:25], v[174:177], v[208:211], v[22:25]
	v_mfma_f32_16x16x32_bf16 v[18:21], v[184:187], v[208:211], v[18:21]
	v_mfma_f32_16x16x32_bf16 v[6:9], v[174:177], v[216:219], v[6:9]
	v_mfma_f32_16x16x32_bf16 v[2:5], v[184:187], v[216:219], v[2:5]
	s_barrier
	s_add_i32 s49, s49, 2
	s_add_u32 s24, s24, 0x100
	s_addc_u32 s25, s25, 0
	s_add_u32 s47, s47, 0x100
	s_addc_u32 s48, s48, 0
	s_cmp_gt_u32 s49, 13
	s_cbranch_scc0 .LBB0_986
	s_and_b64 vcc, exec, s[8:9]
	s_cbranch_vccz .LBB0_989
	s_barrier

.LBB0_1054:
	ds_read_b128 v[148:151], v155
	ds_read_b128 v[158:161], v155 offset:1024
	ds_read_b128 v[162:165], v155 offset:2048
	ds_read_b128 v[166:169], v155 offset:3072
	ds_read_b128 v[170:173], v156
	ds_read_b128 v[174:177], v156 offset:1024
	ds_read_b128 v[180:183], v156 offset:2048
	ds_read_b128 v[184:187], v156 offset:3072
	s_add_u32 s26, s24, 0xfffc0080
	s_addc_u32 s27, s25, -1
	s_cmp_eq_u32 s50, 12
	s_cselect_b32 s29, s17, s27
	s_cselect_b32 s28, s46, s26
	s_cselect_b32 s27, s15, s49
	s_cselect_b32 s26, s47, s48
	v_lshl_add_u64 v[220:221], s[24:25], 0, v[138:139]
	s_add_i32 m0, s23, 0xc000
	ds_read_b128 v[188:191], v157
	ds_read_b128 v[192:195], v157 offset:1024
	ds_read_b128 v[196:199], v157 offset:2048
	ds_read_b128 v[200:203], v157 offset:3072
	ds_read_b128 v[204:207], v157 offset:4096
	ds_read_b128 v[208:211], v157 offset:5120
	ds_read_b128 v[212:215], v157 offset:6144
	ds_read_b128 v[216:219], v157 offset:7168
	global_load_lds_dwordx4 v[220:221], off
	v_lshl_add_u64 v[220:221], s[24:25], 0, v[140:141]
	s_add_i32 m0, s23, 0xe000
	s_nop 0
	global_load_lds_dwordx4 v[220:221], off
	s_waitcnt vmcnt(8)
	s_waitcnt lgkmcnt(0)
	s_barrier
	v_mfma_f32_16x16x32_bf16 v[118:121], v[148:151], v[188:191], v[118:121]
	v_mfma_f32_16x16x32_bf16 v[114:117], v[162:165], v[188:191], v[114:117]
	v_mfma_f32_16x16x32_bf16 v[102:105], v[148:151], v[196:199], v[102:105]
	v_mfma_f32_16x16x32_bf16 v[98:101], v[162:165], v[196:199], v[98:101]
	v_mfma_f32_16x16x32_bf16 v[86:89], v[148:151], v[204:207], v[86:89]
	v_mfma_f32_16x16x32_bf16 v[82:85], v[162:165], v[204:207], v[82:85]
	v_mfma_f32_16x16x32_bf16 v[70:73], v[148:151], v[212:215], v[70:73]
	v_mfma_f32_16x16x32_bf16 v[66:69], v[162:165], v[212:215], v[66:69]
	v_mfma_f32_16x16x32_bf16 v[118:121], v[158:161], v[192:195], v[118:121]
	v_mfma_f32_16x16x32_bf16 v[114:117], v[166:169], v[192:195], v[114:117]
	v_mfma_f32_16x16x32_bf16 v[102:105], v[158:161], v[200:203], v[102:105]
	v_mfma_f32_16x16x32_bf16 v[98:101], v[166:169], v[200:203], v[98:101]
	v_mfma_f32_16x16x32_bf16 v[86:89], v[158:161], v[208:211], v[86:89]
	v_mfma_f32_16x16x32_bf16 v[82:85], v[166:169], v[208:211], v[82:85]
	v_mfma_f32_16x16x32_bf16 v[70:73], v[158:161], v[216:219], v[70:73]
	v_mfma_f32_16x16x32_bf16 v[66:69], v[166:169], v[216:219], v[66:69]
	v_mfma_f32_16x16x32_bf16 v[126:129], v[170:173], v[188:191], v[126:129]
	v_mfma_f32_16x16x32_bf16 v[122:125], v[180:183], v[188:191], v[122:125]
	v_mfma_f32_16x16x32_bf16 v[110:113], v[170:173], v[196:199], v[110:113]
	v_mfma_f32_16x16x32_bf16 v[106:109], v[180:183], v[196:199], v[106:109]
	v_mfma_f32_16x16x32_bf16 v[94:97], v[170:173], v[204:207], v[94:97]
	v_mfma_f32_16x16x32_bf16 v[90:93], v[180:183], v[204:207], v[90:93]
	v_mfma_f32_16x16x32_bf16 v[78:81], v[170:173], v[212:215], v[78:81]
	v_mfma_f32_16x16x32_bf16 v[74:77], v[180:183], v[212:215], v[74:77]
	v_mfma_f32_16x16x32_bf16 v[126:129], v[174:177], v[192:195], v[126:129]
	v_mfma_f32_16x16x32_bf16 v[122:125], v[184:187], v[192:195], v[122:125]
	v_mfma_f32_16x16x32_bf16 v[110:113], v[174:177], v[200:203], v[110:113]
	v_mfma_f32_16x16x32_bf16 v[106:109], v[184:187], v[200:203], v[106:109]
	v_mfma_f32_16x16x32_bf16 v[94:97], v[174:177], v[208:211], v[94:97]
	v_mfma_f32_16x16x32_bf16 v[90:93], v[184:187], v[208:211], v[90:93]
	v_mfma_f32_16x16x32_bf16 v[78:81], v[174:177], v[216:219], v[78:81]
	v_mfma_f32_16x16x32_bf16 v[74:77], v[184:187], v[216:219], v[74:77]
	s_barrier
	s_add_i32 s51, s42, s30
	v_lshl_add_u64 v[220:221], s[26:27], 0, v[134:135]
	s_mov_b32 m0, s51
	ds_read_b128 v[188:191], v157 offset:16384
	ds_read_b128 v[192:195], v157 offset:17408
	ds_read_b128 v[196:199], v157 offset:18432
	ds_read_b128 v[200:203], v157 offset:19456
	ds_read_b128 v[204:207], v157 offset:20480
	ds_read_b128 v[208:211], v157 offset:21504
	ds_read_b128 v[212:215], v157 offset:22528
	ds_read_b128 v[216:219], v157 offset:23552
	global_load_lds_dwordx4 v[220:221], off
	s_add_i32 m0, s51, 0x2000
	s_add_u32 s56, s26, 0x40000
	v_lshl_add_u64 v[222:223], s[26:27], 0, v[130:131]
	s_addc_u32 s57, s27, 0
	s_add_i32 s51, s43, s30
	global_load_lds_dwordx4 v[222:223], off
	v_lshl_add_u64 v[224:225], s[56:57], 0, v[134:135]
	s_mov_b32 m0, s51
	v_lshl_add_u64 v[226:227], s[28:29], 0, v[132:133]
	global_load_lds_dwordx4 v[224:225], off
	v_lshl_add_u64 v[224:225], s[56:57], 0, v[130:131]
	s_add_i32 m0, s51, 0x2000
	s_nop 0
	global_load_lds_dwordx4 v[224:225], off
	v_lshl_add_u64 v[224:225], s[28:29], 0, v[136:137]
	s_mov_b32 m0, s23
	s_nop 0
	global_load_lds_dwordx4 v[224:225], off
	s_mov_b32 m0, s34
	s_nop 0
	global_load_lds_dwordx4 v[226:227], off
	s_waitcnt vmcnt(8)
	s_waitcnt lgkmcnt(0)
	s_barrier
	v_mfma_f32_16x16x32_bf16 v[54:57], v[148:151], v[188:191], v[54:57]
	v_mfma_f32_16x16x32_bf16 v[50:53], v[162:165], v[188:191], v[50:53]
	v_mfma_f32_16x16x32_bf16 v[38:41], v[148:151], v[196:199], v[38:41]
	v_mfma_f32_16x16x32_bf16 v[34:37], v[162:165], v[196:199], v[34:37]
	v_mfma_f32_16x16x32_bf16 v[22:25], v[148:151], v[204:207], v[22:25]
	v_mfma_f32_16x16x32_bf16 v[18:21], v[162:165], v[204:207], v[18:21]
	v_mfma_f32_16x16x32_bf16 v[6:9], v[148:151], v[212:215], v[6:9]
	v_mfma_f32_16x16x32_bf16 v[2:5], v[162:165], v[212:215], v[2:5]
	v_mfma_f32_16x16x32_bf16 v[54:57], v[158:161], v[192:195], v[54:57]
	v_mfma_f32_16x16x32_bf16 v[50:53], v[166:169], v[192:195], v[50:53]
	v_mfma_f32_16x16x32_bf16 v[38:41], v[158:161], v[200:203], v[38:41]
	v_mfma_f32_16x16x32_bf16 v[34:37], v[166:169], v[200:203], v[34:37]
	v_mfma_f32_16x16x32_bf16 v[22:25], v[158:161], v[208:211], v[22:25]
	v_mfma_f32_16x16x32_bf16 v[18:21], v[166:169], v[208:211], v[18:21]
	v_mfma_f32_16x16x32_bf16 v[6:9], v[158:161], v[216:219], v[6:9]
	v_mfma_f32_16x16x32_bf16 v[2:5], v[166:169], v[216:219], v[2:5]
	v_mfma_f32_16x16x32_bf16 v[62:65], v[170:173], v[188:191], v[62:65]
	v_mfma_f32_16x16x32_bf16 v[58:61], v[180:183], v[188:191], v[58:61]
	v_mfma_f32_16x16x32_bf16 v[46:49], v[170:173], v[196:199], v[46:49]
	v_mfma_f32_16x16x32_bf16 v[42:45], v[180:183], v[196:199], v[42:45]
	v_mfma_f32_16x16x32_bf16 v[30:33], v[170:173], v[204:207], v[30:33]
	v_mfma_f32_16x16x32_bf16 v[26:29], v[180:183], v[204:207], v[26:29]
	v_mfma_f32_16x16x32_bf16 v[14:17], v[170:173], v[212:215], v[14:17]
	v_mfma_f32_16x16x32_bf16 v[10:13], v[180:183], v[212:215], v[10:13]
	v_mfma_f32_16x16x32_bf16 v[62:65], v[174:177], v[192:195], v[62:65]
	v_mfma_f32_16x16x32_bf16 v[58:61], v[184:187], v[192:195], v[58:61]
	v_mfma_f32_16x16x32_bf16 v[46:49], v[174:177], v[200:203], v[46:49]
	v_mfma_f32_16x16x32_bf16 v[42:45], v[184:187], v[200:203], v[42:45]
	v_mfma_f32_16x16x32_bf16 v[30:33], v[174:177], v[208:211], v[30:33]
	v_mfma_f32_16x16x32_bf16 v[26:29], v[184:187], v[208:211], v[26:29]
	v_mfma_f32_16x16x32_bf16 v[14:17], v[174:177], v[216:219], v[14:17]
	v_mfma_f32_16x16x32_bf16 v[10:13], v[184:187], v[216:219], v[10:13]
	s_barrier
	s_add_i32 s51, 0, 0x18000
	s_add_i32 s56, 0, 0x1c000
	v_add_u32_e32 v166, s51, v153
	v_add_u32_e32 v179, s56, v153
	ds_read_b128 v[148:151], v166
	ds_read_b128 v[158:161], v166 offset:1024
	ds_read_b128 v[162:165], v166 offset:2048
	ds_read_b128 v[166:169], v166 offset:3072
	ds_read_b128 v[170:173], v179
	ds_read_b128 v[174:177], v179 offset:1024
	ds_read_b128 v[180:183], v179 offset:2048
	ds_read_b128 v[184:187], v179 offset:3072
	s_add_u32 s28, s28, 0x40000
	s_addc_u32 s29, s29, 0
	s_mov_b32 m0, s35
	v_lshl_add_u64 v[228:229], s[28:29], 0, v[136:137]
	ds_read_b128 v[188:191], v157 offset:32768
	ds_read_b128 v[192:195], v157 offset:33792
	ds_read_b128 v[196:199], v157 offset:34816
	ds_read_b128 v[200:203], v157 offset:35840
	ds_read_b128 v[204:207], v157 offset:36864
	ds_read_b128 v[208:211], v157 offset:37888
	ds_read_b128 v[212:215], v157 offset:38912
	ds_read_b128 v[216:219], v157 offset:39936
	global_load_lds_dwordx4 v[228:229], off
	v_lshl_add_u64 v[228:229], s[28:29], 0, v[132:133]
	s_mov_b32 m0, s36
	s_nop 0
	global_load_lds_dwordx4 v[228:229], off
	s_waitcnt vmcnt(8)
	s_waitcnt lgkmcnt(0)
	s_barrier
	v_mfma_f32_16x16x32_bf16 v[118:121], v[148:151], v[188:191], v[118:121]
	v_mfma_f32_16x16x32_bf16 v[114:117], v[162:165], v[188:191], v[114:117]
	v_mfma_f32_16x16x32_bf16 v[102:105], v[148:151], v[196:199], v[102:105]
	v_mfma_f32_16x16x32_bf16 v[98:101], v[162:165], v[196:199], v[98:101]
	v_mfma_f32_16x16x32_bf16 v[86:89], v[148:151], v[204:207], v[86:89]
	v_mfma_f32_16x16x32_bf16 v[82:85], v[162:165], v[204:207], v[82:85]
	v_mfma_f32_16x16x32_bf16 v[70:73], v[148:151], v[212:215], v[70:73]
	v_mfma_f32_16x16x32_bf16 v[66:69], v[162:165], v[212:215], v[66:69]
	v_mfma_f32_16x16x32_bf16 v[118:121], v[158:161], v[192:195], v[118:121]
	v_mfma_f32_16x16x32_bf16 v[114:117], v[166:169], v[192:195], v[114:117]
	v_mfma_f32_16x16x32_bf16 v[102:105], v[158:161], v[200:203], v[102:105]
	v_mfma_f32_16x16x32_bf16 v[98:101], v[166:169], v[200:203], v[98:101]
	v_mfma_f32_16x16x32_bf16 v[86:89], v[158:161], v[208:211], v[86:89]
	v_mfma_f32_16x16x32_bf16 v[82:85], v[166:169], v[208:211], v[82:85]
	v_mfma_f32_16x16x32_bf16 v[70:73], v[158:161], v[216:219], v[70:73]
	v_mfma_f32_16x16x32_bf16 v[66:69], v[166:169], v[216:219], v[66:69]
	v_mfma_f32_16x16x32_bf16 v[126:129], v[170:173], v[188:191], v[126:129]
	v_mfma_f32_16x16x32_bf16 v[122:125], v[180:183], v[188:191], v[122:125]
	v_mfma_f32_16x16x32_bf16 v[110:113], v[170:173], v[196:199], v[110:113]
	v_mfma_f32_16x16x32_bf16 v[106:109], v[180:183], v[196:199], v[106:109]
	v_mfma_f32_16x16x32_bf16 v[94:97], v[170:173], v[204:207], v[94:97]
	v_mfma_f32_16x16x32_bf16 v[90:93], v[180:183], v[204:207], v[90:93]
	v_mfma_f32_16x16x32_bf16 v[78:81], v[170:173], v[212:215], v[78:81]
	v_mfma_f32_16x16x32_bf16 v[74:77], v[180:183], v[212:215], v[74:77]
	v_mfma_f32_16x16x32_bf16 v[126:129], v[174:177], v[192:195], v[126:129]
	v_mfma_f32_16x16x32_bf16 v[122:125], v[184:187], v[192:195], v[122:125]
	v_mfma_f32_16x16x32_bf16 v[110:113], v[174:177], v[200:203], v[110:113]
	v_mfma_f32_16x16x32_bf16 v[106:109], v[184:187], v[200:203], v[106:109]
	v_mfma_f32_16x16x32_bf16 v[94:97], v[174:177], v[208:211], v[94:97]
	v_mfma_f32_16x16x32_bf16 v[90:93], v[184:187], v[208:211], v[90:93]
	v_mfma_f32_16x16x32_bf16 v[78:81], v[174:177], v[216:219], v[78:81]
	v_mfma_f32_16x16x32_bf16 v[74:77], v[184:187], v[216:219], v[74:77]
	s_barrier
	s_add_i32 s28, s51, s30
	v_lshl_add_u64 v[220:221], v[220:221], 0, s[2:3]
	s_mov_b32 m0, s28
	ds_read_b128 v[188:191], v157 offset:49152
	ds_read_b128 v[192:195], v157 offset:50176
	ds_read_b128 v[196:199], v157 offset:51200
	ds_read_b128 v[200:203], v157 offset:52224
	ds_read_b128 v[204:207], v157 offset:53248
	ds_read_b128 v[208:211], v157 offset:54272
	ds_read_b128 v[212:215], v157 offset:55296
	ds_read_b128 v[216:219], v157 offset:56320
	global_load_lds_dwordx4 v[220:221], off
	s_add_i32 m0, s28, 0x2000
	s_add_u32 s26, s26, 0x40080
	v_lshl_add_u64 v[220:221], v[222:223], 0, s[2:3]
	s_addc_u32 s27, s27, 0
	s_add_i32 s28, s56, s30
	global_load_lds_dwordx4 v[220:221], off
	v_lshl_add_u64 v[220:221], s[26:27], 0, v[134:135]
	s_mov_b32 m0, s28
	s_nop 0
	global_load_lds_dwordx4 v[220:221], off
	v_lshl_add_u64 v[220:221], s[26:27], 0, v[130:131]
	s_add_i32 m0, s28, 0x2000
	s_nop 0
	global_load_lds_dwordx4 v[220:221], off
	v_lshl_add_u64 v[220:221], v[224:225], 0, s[2:3]
	s_mov_b32 m0, s38
	s_nop 0
	global_load_lds_dwordx4 v[220:221], off
	v_lshl_add_u64 v[220:221], v[226:227], 0, s[2:3]
	s_mov_b32 m0, s39
	s_nop 0
	global_load_lds_dwordx4 v[220:221], off
	s_waitcnt vmcnt(8)
	s_waitcnt lgkmcnt(0)
	s_barrier
	v_mfma_f32_16x16x32_bf16 v[54:57], v[148:151], v[188:191], v[54:57]
	v_mfma_f32_16x16x32_bf16 v[50:53], v[162:165], v[188:191], v[50:53]
	v_mfma_f32_16x16x32_bf16 v[38:41], v[148:151], v[196:199], v[38:41]
	v_mfma_f32_16x16x32_bf16 v[34:37], v[162:165], v[196:199], v[34:37]
	v_mfma_f32_16x16x32_bf16 v[22:25], v[148:151], v[204:207], v[22:25]
	v_mfma_f32_16x16x32_bf16 v[18:21], v[162:165], v[204:207], v[18:21]
	v_mfma_f32_16x16x32_bf16 v[6:9], v[148:151], v[212:215], v[6:9]
	v_mfma_f32_16x16x32_bf16 v[2:5], v[162:165], v[212:215], v[2:5]
	v_mfma_f32_16x16x32_bf16 v[54:57], v[158:161], v[192:195], v[54:57]
	v_mfma_f32_16x16x32_bf16 v[50:53], v[166:169], v[192:195], v[50:53]
	v_mfma_f32_16x16x32_bf16 v[38:41], v[158:161], v[200:203], v[38:41]
	v_mfma_f32_16x16x32_bf16 v[34:37], v[166:169], v[200:203], v[34:37]
	v_mfma_f32_16x16x32_bf16 v[22:25], v[158:161], v[208:211], v[22:25]
	v_mfma_f32_16x16x32_bf16 v[18:21], v[166:169], v[208:211], v[18:21]
	v_mfma_f32_16x16x32_bf16 v[6:9], v[158:161], v[216:219], v[6:9]
	v_mfma_f32_16x16x32_bf16 v[2:5], v[166:169], v[216:219], v[2:5]
	v_mfma_f32_16x16x32_bf16 v[62:65], v[170:173], v[188:191], v[62:65]
	v_mfma_f32_16x16x32_bf16 v[58:61], v[180:183], v[188:191], v[58:61]
	v_mfma_f32_16x16x32_bf16 v[46:49], v[170:173], v[196:199], v[46:49]
	v_mfma_f32_16x16x32_bf16 v[42:45], v[180:183], v[196:199], v[42:45]
	v_mfma_f32_16x16x32_bf16 v[30:33], v[170:173], v[204:207], v[30:33]
	v_mfma_f32_16x16x32_bf16 v[26:29], v[180:183], v[204:207], v[26:29]
	v_mfma_f32_16x16x32_bf16 v[14:17], v[170:173], v[212:215], v[14:17]
	v_mfma_f32_16x16x32_bf16 v[10:13], v[180:183], v[212:215], v[10:13]
	v_mfma_f32_16x16x32_bf16 v[62:65], v[174:177], v[192:195], v[62:65]
	v_mfma_f32_16x16x32_bf16 v[58:61], v[184:187], v[192:195], v[58:61]
	v_mfma_f32_16x16x32_bf16 v[46:49], v[174:177], v[200:203], v[46:49]
	v_mfma_f32_16x16x32_bf16 v[42:45], v[184:187], v[200:203], v[42:45]
	v_mfma_f32_16x16x32_bf16 v[30:33], v[174:177], v[208:211], v[30:33]
	v_mfma_f32_16x16x32_bf16 v[26:29], v[184:187], v[208:211], v[26:29]
	v_mfma_f32_16x16x32_bf16 v[14:17], v[174:177], v[216:219], v[14:17]
	v_mfma_f32_16x16x32_bf16 v[10:13], v[184:187], v[216:219], v[10:13]
	s_barrier
	s_add_i32 s50, s50, 2
	s_add_u32 s24, s24, 0x100
	s_addc_u32 s25, s25, 0
	s_add_u32 s48, s48, 0x100
	s_addc_u32 s49, s49, 0
	s_cmp_gt_u32 s50, 13
	s_cbranch_scc0 .LBB0_1054
	s_and_b64 vcc, exec, s[8:9]
	s_cbranch_vccz .LBB0_1057
	s_barrier

.LBB0_1124:
	ds_read_b128 v[86:89], v182
	ds_read_b128 v[90:93], v182 offset:1024
	ds_read_b128 v[98:101], v182 offset:2048
	ds_read_b128 v[102:105], v182 offset:3072
	ds_read_b128 v[164:167], v183
	ds_read_b128 v[168:171], v183 offset:1024
	ds_read_b128 v[172:175], v183 offset:2048
	ds_read_b128 v[186:189], v183 offset:3072
	s_add_u32 s34, s30, 0xfff80080
	s_addc_u32 s35, s31, -1
	s_cmp_eq_u32 s59, 28
	s_cselect_b32 s37, s21, s35
	s_cselect_b32 s36, s27, s34
	s_cselect_b32 s35, s19, s58
	s_cselect_b32 s34, s29, s57
	v_lshl_add_u64 v[176:177], s[30:31], 0, v[156:157]
	s_add_i32 m0, s38, 0xc000
	ds_read_b128 v[190:193], v184
	ds_read_b128 v[194:197], v184 offset:1024
	ds_read_b128 v[198:201], v184 offset:2048
	ds_read_b128 v[202:205], v184 offset:3072
	ds_read_b128 v[206:209], v184 offset:4096
	ds_read_b128 v[210:213], v184 offset:5120
	ds_read_b128 v[214:217], v184 offset:6144
	ds_read_b128 v[218:221], v184 offset:7168
	global_load_lds_dwordx4 v[176:177], off
	v_lshl_add_u64 v[176:177], s[30:31], 0, v[158:159]
	s_add_i32 m0, s38, 0xe000
	s_nop 0
	global_load_lds_dwordx4 v[176:177], off
	s_waitcnt vmcnt(8)
	s_waitcnt lgkmcnt(0)
	s_barrier
	v_mfma_f32_16x16x32_bf16 v[142:145], v[86:89], v[190:193], v[142:145]
	v_mfma_f32_16x16x32_bf16 v[138:141], v[98:101], v[190:193], v[138:141]
	v_mfma_f32_16x16x32_bf16 v[126:129], v[86:89], v[198:201], v[126:129]
	v_mfma_f32_16x16x32_bf16 v[122:125], v[98:101], v[198:201], v[122:125]
	v_mfma_f32_16x16x32_bf16 v[110:113], v[86:89], v[206:209], v[110:113]
	v_mfma_f32_16x16x32_bf16 v[106:109], v[98:101], v[206:209], v[106:109]
	v_mfma_f32_16x16x32_bf16 v[78:81], v[86:89], v[214:217], v[78:81]
	v_mfma_f32_16x16x32_bf16 v[74:77], v[98:101], v[214:217], v[74:77]
	v_mfma_f32_16x16x32_bf16 v[142:145], v[90:93], v[194:197], v[142:145]
	v_mfma_f32_16x16x32_bf16 v[138:141], v[102:105], v[194:197], v[138:141]
	v_mfma_f32_16x16x32_bf16 v[126:129], v[90:93], v[202:205], v[126:129]
	v_mfma_f32_16x16x32_bf16 v[122:125], v[102:105], v[202:205], v[122:125]
	v_mfma_f32_16x16x32_bf16 v[110:113], v[90:93], v[210:213], v[110:113]
	v_mfma_f32_16x16x32_bf16 v[106:109], v[102:105], v[210:213], v[106:109]
	v_mfma_f32_16x16x32_bf16 v[78:81], v[90:93], v[218:221], v[78:81]
	v_mfma_f32_16x16x32_bf16 v[74:77], v[102:105], v[218:221], v[74:77]
	v_mfma_f32_16x16x32_bf16 v[134:137], v[164:167], v[190:193], v[134:137]
	v_mfma_f32_16x16x32_bf16 v[130:133], v[172:175], v[190:193], v[130:133]
	v_mfma_f32_16x16x32_bf16 v[118:121], v[164:167], v[198:201], v[118:121]
	v_mfma_f32_16x16x32_bf16 v[114:117], v[172:175], v[198:201], v[114:117]
	v_mfma_f32_16x16x32_bf16 v[94:97], v[164:167], v[206:209], v[94:97]
	v_mfma_f32_16x16x32_bf16 v[82:85], v[172:175], v[206:209], v[82:85]
	v_mfma_f32_16x16x32_bf16 v[70:73], v[164:167], v[214:217], v[70:73]
	v_mfma_f32_16x16x32_bf16 v[66:69], v[172:175], v[214:217], v[66:69]
	v_mfma_f32_16x16x32_bf16 v[134:137], v[168:171], v[194:197], v[134:137]
	v_mfma_f32_16x16x32_bf16 v[130:133], v[186:189], v[194:197], v[130:133]
	v_mfma_f32_16x16x32_bf16 v[118:121], v[168:171], v[202:205], v[118:121]
	v_mfma_f32_16x16x32_bf16 v[114:117], v[186:189], v[202:205], v[114:117]
	v_mfma_f32_16x16x32_bf16 v[94:97], v[168:171], v[210:213], v[94:97]
	v_mfma_f32_16x16x32_bf16 v[82:85], v[186:189], v[210:213], v[82:85]
	v_mfma_f32_16x16x32_bf16 v[70:73], v[168:171], v[218:221], v[70:73]
	v_mfma_f32_16x16x32_bf16 v[66:69], v[186:189], v[218:221], v[66:69]
	s_barrier
	s_add_i32 s68, s51, s33
	v_lshl_add_u64 v[176:177], s[34:35], 0, v[150:151]
	s_mov_b32 m0, s68
	ds_read_b128 v[190:193], v184 offset:16384
	ds_read_b128 v[194:197], v184 offset:17408
	ds_read_b128 v[198:201], v184 offset:18432
	ds_read_b128 v[202:205], v184 offset:19456
	ds_read_b128 v[206:209], v184 offset:20480
	ds_read_b128 v[210:213], v184 offset:21504
	ds_read_b128 v[214:217], v184 offset:22528
	ds_read_b128 v[218:221], v184 offset:23552
	global_load_lds_dwordx4 v[176:177], off
	s_add_i32 m0, s68, 0x2000
	s_add_u32 s68, s34, 0x80000
	v_lshl_add_u64 v[222:223], s[34:35], 0, v[154:155]
	s_addc_u32 s69, s35, 0
	s_add_i32 s70, s56, s33
	global_load_lds_dwordx4 v[222:223], off
	v_lshl_add_u64 v[224:225], s[68:69], 0, v[150:151]
	s_mov_b32 m0, s70
	v_lshl_add_u64 v[226:227], s[36:37], 0, v[152:153]
	global_load_lds_dwordx4 v[224:225], off
	v_lshl_add_u64 v[224:225], s[68:69], 0, v[154:155]
	s_add_i32 m0, s70, 0x2000
	s_nop 0
	global_load_lds_dwordx4 v[224:225], off
	v_lshl_add_u64 v[224:225], s[36:37], 0, v[148:149]
	s_mov_b32 m0, s38
	s_nop 0
	global_load_lds_dwordx4 v[224:225], off
	s_mov_b32 m0, s39
	s_nop 0
	global_load_lds_dwordx4 v[226:227], off
	s_waitcnt vmcnt(8)
	s_waitcnt lgkmcnt(0)
	s_barrier
	v_mfma_f32_16x16x32_bf16 v[62:65], v[86:89], v[190:193], v[62:65]
	v_mfma_f32_16x16x32_bf16 v[58:61], v[98:101], v[190:193], v[58:61]
	v_mfma_f32_16x16x32_bf16 v[46:49], v[86:89], v[198:201], v[46:49]
	v_mfma_f32_16x16x32_bf16 v[42:45], v[98:101], v[198:201], v[42:45]
	v_mfma_f32_16x16x32_bf16 v[30:33], v[86:89], v[206:209], v[30:33]
	v_mfma_f32_16x16x32_bf16 v[26:29], v[98:101], v[206:209], v[26:29]
	v_mfma_f32_16x16x32_bf16 v[14:17], v[86:89], v[214:217], v[14:17]
	v_mfma_f32_16x16x32_bf16 v[10:13], v[98:101], v[214:217], v[10:13]
	v_mfma_f32_16x16x32_bf16 v[62:65], v[90:93], v[194:197], v[62:65]
	v_mfma_f32_16x16x32_bf16 v[58:61], v[102:105], v[194:197], v[58:61]
	v_mfma_f32_16x16x32_bf16 v[46:49], v[90:93], v[202:205], v[46:49]
	v_mfma_f32_16x16x32_bf16 v[42:45], v[102:105], v[202:205], v[42:45]
	v_mfma_f32_16x16x32_bf16 v[30:33], v[90:93], v[210:213], v[30:33]
	v_mfma_f32_16x16x32_bf16 v[26:29], v[102:105], v[210:213], v[26:29]
	v_mfma_f32_16x16x32_bf16 v[14:17], v[90:93], v[218:221], v[14:17]
	v_mfma_f32_16x16x32_bf16 v[10:13], v[102:105], v[218:221], v[10:13]
	v_mfma_f32_16x16x32_bf16 v[54:57], v[164:167], v[190:193], v[54:57]
	v_mfma_f32_16x16x32_bf16 v[50:53], v[172:175], v[190:193], v[50:53]
	v_mfma_f32_16x16x32_bf16 v[38:41], v[164:167], v[198:201], v[38:41]
	v_mfma_f32_16x16x32_bf16 v[34:37], v[172:175], v[198:201], v[34:37]
	v_mfma_f32_16x16x32_bf16 v[22:25], v[164:167], v[206:209], v[22:25]
	v_mfma_f32_16x16x32_bf16 v[18:21], v[172:175], v[206:209], v[18:21]
	v_mfma_f32_16x16x32_bf16 v[6:9], v[164:167], v[214:217], v[6:9]
	v_mfma_f32_16x16x32_bf16 v[2:5], v[172:175], v[214:217], v[2:5]
	v_mfma_f32_16x16x32_bf16 v[54:57], v[168:171], v[194:197], v[54:57]
	v_mfma_f32_16x16x32_bf16 v[50:53], v[186:189], v[194:197], v[50:53]
	v_mfma_f32_16x16x32_bf16 v[38:41], v[168:171], v[202:205], v[38:41]
	v_mfma_f32_16x16x32_bf16 v[34:37], v[186:189], v[202:205], v[34:37]
	v_mfma_f32_16x16x32_bf16 v[22:25], v[168:171], v[210:213], v[22:25]
	v_mfma_f32_16x16x32_bf16 v[18:21], v[186:189], v[210:213], v[18:21]
	v_mfma_f32_16x16x32_bf16 v[6:9], v[168:171], v[218:221], v[6:9]
	v_mfma_f32_16x16x32_bf16 v[2:5], v[186:189], v[218:221], v[2:5]
	s_barrier
	s_add_i32 s68, 0, 0x18000
	s_add_i32 s69, 0, 0x1c000
	v_add_u32_e32 v102, s68, v180
	v_add_u32_e32 v185, s69, v180
	ds_read_b128 v[86:89], v102
	ds_read_b128 v[90:93], v102 offset:1024
	ds_read_b128 v[98:101], v102 offset:2048
	ds_read_b128 v[102:105], v102 offset:3072
	ds_read_b128 v[164:167], v185
	ds_read_b128 v[168:171], v185 offset:1024
	ds_read_b128 v[172:175], v185 offset:2048
	ds_read_b128 v[186:189], v185 offset:3072
	s_add_u32 s36, s36, 0x80000
	s_addc_u32 s37, s37, 0
	s_mov_b32 m0, s40
	v_lshl_add_u64 v[228:229], s[36:37], 0, v[148:149]
	ds_read_b128 v[190:193], v184 offset:32768
	ds_read_b128 v[194:197], v184 offset:33792
	ds_read_b128 v[198:201], v184 offset:34816
	ds_read_b128 v[202:205], v184 offset:35840
	ds_read_b128 v[206:209], v184 offset:36864
	ds_read_b128 v[210:213], v184 offset:37888
	ds_read_b128 v[214:217], v184 offset:38912
	ds_read_b128 v[218:221], v184 offset:39936
	global_load_lds_dwordx4 v[228:229], off
	v_lshl_add_u64 v[228:229], s[36:37], 0, v[152:153]
	s_mov_b32 m0, s41
	s_nop 0
	global_load_lds_dwordx4 v[228:229], off
	s_waitcnt vmcnt(8)
	s_waitcnt lgkmcnt(0)
	s_barrier
	v_mfma_f32_16x16x32_bf16 v[142:145], v[86:89], v[190:193], v[142:145]
	v_mfma_f32_16x16x32_bf16 v[138:141], v[98:101], v[190:193], v[138:141]
	v_mfma_f32_16x16x32_bf16 v[126:129], v[86:89], v[198:201], v[126:129]
	v_mfma_f32_16x16x32_bf16 v[122:125], v[98:101], v[198:201], v[122:125]
	v_mfma_f32_16x16x32_bf16 v[110:113], v[86:89], v[206:209], v[110:113]
	v_mfma_f32_16x16x32_bf16 v[106:109], v[98:101], v[206:209], v[106:109]
	v_mfma_f32_16x16x32_bf16 v[78:81], v[86:89], v[214:217], v[78:81]
	v_mfma_f32_16x16x32_bf16 v[74:77], v[98:101], v[214:217], v[74:77]
	v_mfma_f32_16x16x32_bf16 v[142:145], v[90:93], v[194:197], v[142:145]
	v_mfma_f32_16x16x32_bf16 v[138:141], v[102:105], v[194:197], v[138:141]
	v_mfma_f32_16x16x32_bf16 v[126:129], v[90:93], v[202:205], v[126:129]
	v_mfma_f32_16x16x32_bf16 v[122:125], v[102:105], v[202:205], v[122:125]
	v_mfma_f32_16x16x32_bf16 v[110:113], v[90:93], v[210:213], v[110:113]
	v_mfma_f32_16x16x32_bf16 v[106:109], v[102:105], v[210:213], v[106:109]
	v_mfma_f32_16x16x32_bf16 v[78:81], v[90:93], v[218:221], v[78:81]
	v_mfma_f32_16x16x32_bf16 v[74:77], v[102:105], v[218:221], v[74:77]
	v_mfma_f32_16x16x32_bf16 v[134:137], v[164:167], v[190:193], v[134:137]
	v_mfma_f32_16x16x32_bf16 v[130:133], v[172:175], v[190:193], v[130:133]
	v_mfma_f32_16x16x32_bf16 v[118:121], v[164:167], v[198:201], v[118:121]
	v_mfma_f32_16x16x32_bf16 v[114:117], v[172:175], v[198:201], v[114:117]
	v_mfma_f32_16x16x32_bf16 v[94:97], v[164:167], v[206:209], v[94:97]
	v_mfma_f32_16x16x32_bf16 v[82:85], v[172:175], v[206:209], v[82:85]
	v_mfma_f32_16x16x32_bf16 v[70:73], v[164:167], v[214:217], v[70:73]
	v_mfma_f32_16x16x32_bf16 v[66:69], v[172:175], v[214:217], v[66:69]
	v_mfma_f32_16x16x32_bf16 v[134:137], v[168:171], v[194:197], v[134:137]
	v_mfma_f32_16x16x32_bf16 v[130:133], v[186:189], v[194:197], v[130:133]
	v_mfma_f32_16x16x32_bf16 v[118:121], v[168:171], v[202:205], v[118:121]
	v_mfma_f32_16x16x32_bf16 v[114:117], v[186:189], v[202:205], v[114:117]
	v_mfma_f32_16x16x32_bf16 v[94:97], v[168:171], v[210:213], v[94:97]
	v_mfma_f32_16x16x32_bf16 v[82:85], v[186:189], v[210:213], v[82:85]
	v_mfma_f32_16x16x32_bf16 v[70:73], v[168:171], v[218:221], v[70:73]
	v_mfma_f32_16x16x32_bf16 v[66:69], v[186:189], v[218:221], v[66:69]
	s_barrier
	s_add_i32 s36, s68, s33
	v_lshl_add_u64 v[176:177], v[176:177], 0, s[2:3]
	s_mov_b32 m0, s36
	ds_read_b128 v[190:193], v184 offset:49152
	ds_read_b128 v[194:197], v184 offset:50176
	ds_read_b128 v[198:201], v184 offset:51200
	ds_read_b128 v[202:205], v184 offset:52224
	ds_read_b128 v[206:209], v184 offset:53248
	ds_read_b128 v[210:213], v184 offset:54272
	ds_read_b128 v[214:217], v184 offset:55296
	ds_read_b128 v[218:221], v184 offset:56320
	global_load_lds_dwordx4 v[176:177], off
	s_add_i32 m0, s36, 0x2000
	s_add_u32 s34, s34, 0x80080
	v_lshl_add_u64 v[176:177], v[222:223], 0, s[2:3]
	s_addc_u32 s35, s35, 0
	s_add_i32 s36, s69, s33
	global_load_lds_dwordx4 v[176:177], off
	v_lshl_add_u64 v[176:177], s[34:35], 0, v[150:151]
	s_mov_b32 m0, s36
	s_nop 0
	global_load_lds_dwordx4 v[176:177], off
	v_lshl_add_u64 v[176:177], s[34:35], 0, v[154:155]
	s_add_i32 m0, s36, 0x2000
	s_nop 0
	global_load_lds_dwordx4 v[176:177], off
	v_lshl_add_u64 v[176:177], v[224:225], 0, s[2:3]
	s_mov_b32 m0, s43
	s_nop 0
	global_load_lds_dwordx4 v[176:177], off
	v_lshl_add_u64 v[176:177], v[226:227], 0, s[2:3]
	s_mov_b32 m0, s44
	s_nop 0
	global_load_lds_dwordx4 v[176:177], off
	s_waitcnt vmcnt(8)
	s_waitcnt lgkmcnt(0)
	s_barrier
	v_mfma_f32_16x16x32_bf16 v[62:65], v[86:89], v[190:193], v[62:65]
	v_mfma_f32_16x16x32_bf16 v[58:61], v[98:101], v[190:193], v[58:61]
	v_mfma_f32_16x16x32_bf16 v[46:49], v[86:89], v[198:201], v[46:49]
	v_mfma_f32_16x16x32_bf16 v[42:45], v[98:101], v[198:201], v[42:45]
	v_mfma_f32_16x16x32_bf16 v[30:33], v[86:89], v[206:209], v[30:33]
	v_mfma_f32_16x16x32_bf16 v[26:29], v[98:101], v[206:209], v[26:29]
	v_mfma_f32_16x16x32_bf16 v[14:17], v[86:89], v[214:217], v[14:17]
	v_mfma_f32_16x16x32_bf16 v[10:13], v[98:101], v[214:217], v[10:13]
	v_mfma_f32_16x16x32_bf16 v[62:65], v[90:93], v[194:197], v[62:65]
	v_mfma_f32_16x16x32_bf16 v[58:61], v[102:105], v[194:197], v[58:61]
	v_mfma_f32_16x16x32_bf16 v[46:49], v[90:93], v[202:205], v[46:49]
	v_mfma_f32_16x16x32_bf16 v[42:45], v[102:105], v[202:205], v[42:45]
	v_mfma_f32_16x16x32_bf16 v[30:33], v[90:93], v[210:213], v[30:33]
	v_mfma_f32_16x16x32_bf16 v[26:29], v[102:105], v[210:213], v[26:29]
	v_mfma_f32_16x16x32_bf16 v[14:17], v[90:93], v[218:221], v[14:17]
	v_mfma_f32_16x16x32_bf16 v[10:13], v[102:105], v[218:221], v[10:13]
	v_mfma_f32_16x16x32_bf16 v[54:57], v[164:167], v[190:193], v[54:57]
	v_mfma_f32_16x16x32_bf16 v[50:53], v[172:175], v[190:193], v[50:53]
	v_mfma_f32_16x16x32_bf16 v[38:41], v[164:167], v[198:201], v[38:41]
	v_mfma_f32_16x16x32_bf16 v[34:37], v[172:175], v[198:201], v[34:37]
	v_mfma_f32_16x16x32_bf16 v[22:25], v[164:167], v[206:209], v[22:25]
	v_mfma_f32_16x16x32_bf16 v[18:21], v[172:175], v[206:209], v[18:21]
	v_mfma_f32_16x16x32_bf16 v[6:9], v[164:167], v[214:217], v[6:9]
	v_mfma_f32_16x16x32_bf16 v[2:5], v[172:175], v[214:217], v[2:5]
	v_mfma_f32_16x16x32_bf16 v[54:57], v[168:171], v[194:197], v[54:57]
	v_mfma_f32_16x16x32_bf16 v[50:53], v[186:189], v[194:197], v[50:53]
	v_mfma_f32_16x16x32_bf16 v[38:41], v[168:171], v[202:205], v[38:41]
	v_mfma_f32_16x16x32_bf16 v[34:37], v[186:189], v[202:205], v[34:37]
	v_mfma_f32_16x16x32_bf16 v[22:25], v[168:171], v[210:213], v[22:25]
	v_mfma_f32_16x16x32_bf16 v[18:21], v[186:189], v[210:213], v[18:21]
	v_mfma_f32_16x16x32_bf16 v[6:9], v[168:171], v[218:221], v[6:9]
	v_mfma_f32_16x16x32_bf16 v[2:5], v[186:189], v[218:221], v[2:5]
	s_barrier
	s_add_i32 s59, s59, 2
	s_add_u32 s30, s30, 0x100
	s_addc_u32 s31, s31, 0
	s_add_u32 s57, s57, 0x100
	s_addc_u32 s58, s58, 0
	s_cmp_gt_u32 s59, 29
	s_cbranch_scc0 .LBB0_1124
	s_and_b64 vcc, exec, s[16:17]
	s_cbranch_vccz .LBB0_1127
	s_barrier

.LBB0_1208:
	ds_read_b128 v[98:101], v175
	ds_read_b128 v[102:105], v175 offset:1024
	ds_read_b128 v[106:109], v175 offset:2048
	ds_read_b128 v[110:113], v175 offset:3072
	ds_read_b128 v[164:167], v176
	ds_read_b128 v[168:171], v176 offset:1024
	ds_read_b128 v[182:185], v176 offset:2048
	ds_read_b128 v[186:189], v176 offset:3072
	s_add_u32 s28, s26, 0xfff80080
	s_addc_u32 s29, s27, -1
	s_cmp_eq_u32 s58, 28
	s_cselect_b32 s31, s21, s29
	s_cselect_b32 s30, s50, s28
	s_cselect_b32 s29, s19, s57
	s_cselect_b32 s28, s51, s56
	v_lshl_add_u64 v[222:223], s[26:27], 0, v[156:157]
	s_add_i32 m0, s36, 0xc000
	ds_read_b128 v[190:193], v177
	ds_read_b128 v[194:197], v177 offset:1024
	ds_read_b128 v[198:201], v177 offset:2048
	ds_read_b128 v[202:205], v177 offset:3072
	ds_read_b128 v[206:209], v177 offset:4096
	ds_read_b128 v[210:213], v177 offset:5120
	ds_read_b128 v[214:217], v177 offset:6144
	ds_read_b128 v[218:221], v177 offset:7168
	global_load_lds_dwordx4 v[222:223], off
	v_lshl_add_u64 v[222:223], s[26:27], 0, v[158:159]
	s_add_i32 m0, s36, 0xe000
	s_nop 0
	global_load_lds_dwordx4 v[222:223], off
	s_waitcnt vmcnt(8)
	s_waitcnt lgkmcnt(0)
	s_barrier
	v_mfma_f32_16x16x32_bf16 v[142:145], v[98:101], v[190:193], v[142:145]
	v_mfma_f32_16x16x32_bf16 v[138:141], v[106:109], v[190:193], v[138:141]
	v_mfma_f32_16x16x32_bf16 v[126:129], v[98:101], v[198:201], v[126:129]
	v_mfma_f32_16x16x32_bf16 v[122:125], v[106:109], v[198:201], v[122:125]
	v_mfma_f32_16x16x32_bf16 v[94:97], v[98:101], v[206:209], v[94:97]
	v_mfma_f32_16x16x32_bf16 v[90:93], v[106:109], v[206:209], v[90:93]
	v_mfma_f32_16x16x32_bf16 v[78:81], v[98:101], v[214:217], v[78:81]
	v_mfma_f32_16x16x32_bf16 v[74:77], v[106:109], v[214:217], v[74:77]
	v_mfma_f32_16x16x32_bf16 v[142:145], v[102:105], v[194:197], v[142:145]
	v_mfma_f32_16x16x32_bf16 v[138:141], v[110:113], v[194:197], v[138:141]
	v_mfma_f32_16x16x32_bf16 v[126:129], v[102:105], v[202:205], v[126:129]
	v_mfma_f32_16x16x32_bf16 v[122:125], v[110:113], v[202:205], v[122:125]
	v_mfma_f32_16x16x32_bf16 v[94:97], v[102:105], v[210:213], v[94:97]
	v_mfma_f32_16x16x32_bf16 v[90:93], v[110:113], v[210:213], v[90:93]
	v_mfma_f32_16x16x32_bf16 v[78:81], v[102:105], v[218:221], v[78:81]
	v_mfma_f32_16x16x32_bf16 v[74:77], v[110:113], v[218:221], v[74:77]
	v_mfma_f32_16x16x32_bf16 v[134:137], v[164:167], v[190:193], v[134:137]
	v_mfma_f32_16x16x32_bf16 v[130:133], v[182:185], v[190:193], v[130:133]
	v_mfma_f32_16x16x32_bf16 v[118:121], v[164:167], v[198:201], v[118:121]
	v_mfma_f32_16x16x32_bf16 v[114:117], v[182:185], v[198:201], v[114:117]
	v_mfma_f32_16x16x32_bf16 v[86:89], v[164:167], v[206:209], v[86:89]
	v_mfma_f32_16x16x32_bf16 v[82:85], v[182:185], v[206:209], v[82:85]
	v_mfma_f32_16x16x32_bf16 v[70:73], v[164:167], v[214:217], v[70:73]
	v_mfma_f32_16x16x32_bf16 v[66:69], v[182:185], v[214:217], v[66:69]
	v_mfma_f32_16x16x32_bf16 v[134:137], v[168:171], v[194:197], v[134:137]
	v_mfma_f32_16x16x32_bf16 v[130:133], v[186:189], v[194:197], v[130:133]
	v_mfma_f32_16x16x32_bf16 v[118:121], v[168:171], v[202:205], v[118:121]
	v_mfma_f32_16x16x32_bf16 v[114:117], v[186:189], v[202:205], v[114:117]
	v_mfma_f32_16x16x32_bf16 v[86:89], v[168:171], v[210:213], v[86:89]
	v_mfma_f32_16x16x32_bf16 v[82:85], v[186:189], v[210:213], v[82:85]
	v_mfma_f32_16x16x32_bf16 v[70:73], v[168:171], v[218:221], v[70:73]
	v_mfma_f32_16x16x32_bf16 v[66:69], v[186:189], v[218:221], v[66:69]
	s_barrier
	s_add_i32 s59, s45, s33
	v_lshl_add_u64 v[222:223], s[28:29], 0, v[152:153]
	s_mov_b32 m0, s59
	ds_read_b128 v[190:193], v177 offset:16384
	ds_read_b128 v[194:197], v177 offset:17408
	ds_read_b128 v[198:201], v177 offset:18432
	ds_read_b128 v[202:205], v177 offset:19456
	ds_read_b128 v[206:209], v177 offset:20480
	ds_read_b128 v[210:213], v177 offset:21504
	ds_read_b128 v[214:217], v177 offset:22528
	ds_read_b128 v[218:221], v177 offset:23552
	global_load_lds_dwordx4 v[222:223], off
	s_add_i32 m0, s59, 0x2000
	s_add_u32 s68, s28, 0x80000
	v_lshl_add_u64 v[224:225], s[28:29], 0, v[148:149]
	s_addc_u32 s69, s29, 0
	s_add_i32 s59, s46, s33
	global_load_lds_dwordx4 v[224:225], off
	v_lshl_add_u64 v[226:227], s[68:69], 0, v[152:153]
	s_mov_b32 m0, s59
	v_lshl_add_u64 v[228:229], s[30:31], 0, v[150:151]
	global_load_lds_dwordx4 v[226:227], off
	v_lshl_add_u64 v[226:227], s[68:69], 0, v[148:149]
	s_add_i32 m0, s59, 0x2000
	s_nop 0
	global_load_lds_dwordx4 v[226:227], off
	v_lshl_add_u64 v[226:227], s[30:31], 0, v[154:155]
	s_mov_b32 m0, s36
	s_nop 0
	global_load_lds_dwordx4 v[226:227], off
	s_mov_b32 m0, s37
	s_nop 0
	global_load_lds_dwordx4 v[228:229], off
	s_waitcnt vmcnt(8)
	s_waitcnt lgkmcnt(0)
	s_barrier
	v_mfma_f32_16x16x32_bf16 v[62:65], v[98:101], v[190:193], v[62:65]
	v_mfma_f32_16x16x32_bf16 v[58:61], v[106:109], v[190:193], v[58:61]
	v_mfma_f32_16x16x32_bf16 v[46:49], v[98:101], v[198:201], v[46:49]
	v_mfma_f32_16x16x32_bf16 v[42:45], v[106:109], v[198:201], v[42:45]
	v_mfma_f32_16x16x32_bf16 v[30:33], v[98:101], v[206:209], v[30:33]
	v_mfma_f32_16x16x32_bf16 v[26:29], v[106:109], v[206:209], v[26:29]
	v_mfma_f32_16x16x32_bf16 v[14:17], v[98:101], v[214:217], v[14:17]
	v_mfma_f32_16x16x32_bf16 v[10:13], v[106:109], v[214:217], v[10:13]
	v_mfma_f32_16x16x32_bf16 v[62:65], v[102:105], v[194:197], v[62:65]
	v_mfma_f32_16x16x32_bf16 v[58:61], v[110:113], v[194:197], v[58:61]
	v_mfma_f32_16x16x32_bf16 v[46:49], v[102:105], v[202:205], v[46:49]
	v_mfma_f32_16x16x32_bf16 v[42:45], v[110:113], v[202:205], v[42:45]
	v_mfma_f32_16x16x32_bf16 v[30:33], v[102:105], v[210:213], v[30:33]
	v_mfma_f32_16x16x32_bf16 v[26:29], v[110:113], v[210:213], v[26:29]
	v_mfma_f32_16x16x32_bf16 v[14:17], v[102:105], v[218:221], v[14:17]
	v_mfma_f32_16x16x32_bf16 v[10:13], v[110:113], v[218:221], v[10:13]
	v_mfma_f32_16x16x32_bf16 v[54:57], v[164:167], v[190:193], v[54:57]
	v_mfma_f32_16x16x32_bf16 v[50:53], v[182:185], v[190:193], v[50:53]
	v_mfma_f32_16x16x32_bf16 v[38:41], v[164:167], v[198:201], v[38:41]
	v_mfma_f32_16x16x32_bf16 v[34:37], v[182:185], v[198:201], v[34:37]
	v_mfma_f32_16x16x32_bf16 v[22:25], v[164:167], v[206:209], v[22:25]
	v_mfma_f32_16x16x32_bf16 v[18:21], v[182:185], v[206:209], v[18:21]
	v_mfma_f32_16x16x32_bf16 v[6:9], v[164:167], v[214:217], v[6:9]
	v_mfma_f32_16x16x32_bf16 v[2:5], v[182:185], v[214:217], v[2:5]
	v_mfma_f32_16x16x32_bf16 v[54:57], v[168:171], v[194:197], v[54:57]
	v_mfma_f32_16x16x32_bf16 v[50:53], v[186:189], v[194:197], v[50:53]
	v_mfma_f32_16x16x32_bf16 v[38:41], v[168:171], v[202:205], v[38:41]
	v_mfma_f32_16x16x32_bf16 v[34:37], v[186:189], v[202:205], v[34:37]
	v_mfma_f32_16x16x32_bf16 v[22:25], v[168:171], v[210:213], v[22:25]
	v_mfma_f32_16x16x32_bf16 v[18:21], v[186:189], v[210:213], v[18:21]
	v_mfma_f32_16x16x32_bf16 v[6:9], v[168:171], v[218:221], v[6:9]
	v_mfma_f32_16x16x32_bf16 v[2:5], v[186:189], v[218:221], v[2:5]
	s_barrier
	s_add_i32 s59, 0, 0x18000
	s_add_i32 s68, 0, 0x1c000
	v_add_u32_e32 v110, s59, v173
	v_add_u32_e32 v181, s68, v173
	ds_read_b128 v[98:101], v110
	ds_read_b128 v[102:105], v110 offset:1024
	ds_read_b128 v[106:109], v110 offset:2048
	ds_read_b128 v[110:113], v110 offset:3072
	ds_read_b128 v[164:167], v181
	ds_read_b128 v[168:171], v181 offset:1024
	ds_read_b128 v[182:185], v181 offset:2048
	ds_read_b128 v[186:189], v181 offset:3072
	s_add_u32 s30, s30, 0x80000
	s_addc_u32 s31, s31, 0
	s_mov_b32 m0, s38
	v_lshl_add_u64 v[230:231], s[30:31], 0, v[154:155]
	ds_read_b128 v[190:193], v177 offset:32768
	ds_read_b128 v[194:197], v177 offset:33792
	ds_read_b128 v[198:201], v177 offset:34816
	ds_read_b128 v[202:205], v177 offset:35840
	ds_read_b128 v[206:209], v177 offset:36864
	ds_read_b128 v[210:213], v177 offset:37888
	ds_read_b128 v[214:217], v177 offset:38912
	ds_read_b128 v[218:221], v177 offset:39936
	global_load_lds_dwordx4 v[230:231], off
	v_lshl_add_u64 v[230:231], s[30:31], 0, v[150:151]
	s_mov_b32 m0, s39
	s_nop 0
	global_load_lds_dwordx4 v[230:231], off
	s_waitcnt vmcnt(8)
	s_waitcnt lgkmcnt(0)
	s_barrier
	v_mfma_f32_16x16x32_bf16 v[142:145], v[98:101], v[190:193], v[142:145]
	v_mfma_f32_16x16x32_bf16 v[138:141], v[106:109], v[190:193], v[138:141]
	v_mfma_f32_16x16x32_bf16 v[126:129], v[98:101], v[198:201], v[126:129]
	v_mfma_f32_16x16x32_bf16 v[122:125], v[106:109], v[198:201], v[122:125]
	v_mfma_f32_16x16x32_bf16 v[94:97], v[98:101], v[206:209], v[94:97]
	v_mfma_f32_16x16x32_bf16 v[90:93], v[106:109], v[206:209], v[90:93]
	v_mfma_f32_16x16x32_bf16 v[78:81], v[98:101], v[214:217], v[78:81]
	v_mfma_f32_16x16x32_bf16 v[74:77], v[106:109], v[214:217], v[74:77]
	v_mfma_f32_16x16x32_bf16 v[142:145], v[102:105], v[194:197], v[142:145]
	v_mfma_f32_16x16x32_bf16 v[138:141], v[110:113], v[194:197], v[138:141]
	v_mfma_f32_16x16x32_bf16 v[126:129], v[102:105], v[202:205], v[126:129]
	v_mfma_f32_16x16x32_bf16 v[122:125], v[110:113], v[202:205], v[122:125]
	v_mfma_f32_16x16x32_bf16 v[94:97], v[102:105], v[210:213], v[94:97]
	v_mfma_f32_16x16x32_bf16 v[90:93], v[110:113], v[210:213], v[90:93]
	v_mfma_f32_16x16x32_bf16 v[78:81], v[102:105], v[218:221], v[78:81]
	v_mfma_f32_16x16x32_bf16 v[74:77], v[110:113], v[218:221], v[74:77]
	v_mfma_f32_16x16x32_bf16 v[134:137], v[164:167], v[190:193], v[134:137]
	v_mfma_f32_16x16x32_bf16 v[130:133], v[182:185], v[190:193], v[130:133]
	v_mfma_f32_16x16x32_bf16 v[118:121], v[164:167], v[198:201], v[118:121]
	v_mfma_f32_16x16x32_bf16 v[114:117], v[182:185], v[198:201], v[114:117]
	v_mfma_f32_16x16x32_bf16 v[86:89], v[164:167], v[206:209], v[86:89]
	v_mfma_f32_16x16x32_bf16 v[82:85], v[182:185], v[206:209], v[82:85]
	v_mfma_f32_16x16x32_bf16 v[70:73], v[164:167], v[214:217], v[70:73]
	v_mfma_f32_16x16x32_bf16 v[66:69], v[182:185], v[214:217], v[66:69]
	v_mfma_f32_16x16x32_bf16 v[134:137], v[168:171], v[194:197], v[134:137]
	v_mfma_f32_16x16x32_bf16 v[130:133], v[186:189], v[194:197], v[130:133]
	v_mfma_f32_16x16x32_bf16 v[118:121], v[168:171], v[202:205], v[118:121]
	v_mfma_f32_16x16x32_bf16 v[114:117], v[186:189], v[202:205], v[114:117]
	v_mfma_f32_16x16x32_bf16 v[86:89], v[168:171], v[210:213], v[86:89]
	v_mfma_f32_16x16x32_bf16 v[82:85], v[186:189], v[210:213], v[82:85]
	v_mfma_f32_16x16x32_bf16 v[70:73], v[168:171], v[218:221], v[70:73]
	v_mfma_f32_16x16x32_bf16 v[66:69], v[186:189], v[218:221], v[66:69]
	s_barrier
	s_add_i32 s30, s59, s33
	v_lshl_add_u64 v[222:223], v[222:223], 0, s[8:9]
	s_mov_b32 m0, s30
	ds_read_b128 v[190:193], v177 offset:49152
	ds_read_b128 v[194:197], v177 offset:50176
	ds_read_b128 v[198:201], v177 offset:51200
	ds_read_b128 v[202:205], v177 offset:52224
	ds_read_b128 v[206:209], v177 offset:53248
	ds_read_b128 v[210:213], v177 offset:54272
	ds_read_b128 v[214:217], v177 offset:55296
	ds_read_b128 v[218:221], v177 offset:56320
	global_load_lds_dwordx4 v[222:223], off
	s_add_i32 m0, s30, 0x2000
	s_add_u32 s28, s28, 0x80080
	v_lshl_add_u64 v[222:223], v[224:225], 0, s[8:9]
	s_addc_u32 s29, s29, 0
	s_add_i32 s30, s68, s33
	global_load_lds_dwordx4 v[222:223], off
	v_lshl_add_u64 v[222:223], s[28:29], 0, v[152:153]
	s_mov_b32 m0, s30
	s_nop 0
	global_load_lds_dwordx4 v[222:223], off
	v_lshl_add_u64 v[222:223], s[28:29], 0, v[148:149]
	s_add_i32 m0, s30, 0x2000
	s_nop 0
	global_load_lds_dwordx4 v[222:223], off
	v_lshl_add_u64 v[222:223], v[226:227], 0, s[8:9]
	s_mov_b32 m0, s41
	s_nop 0
	global_load_lds_dwordx4 v[222:223], off
	v_lshl_add_u64 v[222:223], v[228:229], 0, s[8:9]
	s_mov_b32 m0, s42
	s_nop 0
	global_load_lds_dwordx4 v[222:223], off
	s_waitcnt vmcnt(8)
	s_waitcnt lgkmcnt(0)
	s_barrier
	v_mfma_f32_16x16x32_bf16 v[62:65], v[98:101], v[190:193], v[62:65]
	v_mfma_f32_16x16x32_bf16 v[58:61], v[106:109], v[190:193], v[58:61]
	v_mfma_f32_16x16x32_bf16 v[46:49], v[98:101], v[198:201], v[46:49]
	v_mfma_f32_16x16x32_bf16 v[42:45], v[106:109], v[198:201], v[42:45]
	v_mfma_f32_16x16x32_bf16 v[30:33], v[98:101], v[206:209], v[30:33]
	v_mfma_f32_16x16x32_bf16 v[26:29], v[106:109], v[206:209], v[26:29]
	v_mfma_f32_16x16x32_bf16 v[14:17], v[98:101], v[214:217], v[14:17]
	v_mfma_f32_16x16x32_bf16 v[10:13], v[106:109], v[214:217], v[10:13]
	v_mfma_f32_16x16x32_bf16 v[62:65], v[102:105], v[194:197], v[62:65]
	v_mfma_f32_16x16x32_bf16 v[58:61], v[110:113], v[194:197], v[58:61]
	v_mfma_f32_16x16x32_bf16 v[46:49], v[102:105], v[202:205], v[46:49]
	v_mfma_f32_16x16x32_bf16 v[42:45], v[110:113], v[202:205], v[42:45]
	v_mfma_f32_16x16x32_bf16 v[30:33], v[102:105], v[210:213], v[30:33]
	v_mfma_f32_16x16x32_bf16 v[26:29], v[110:113], v[210:213], v[26:29]
	v_mfma_f32_16x16x32_bf16 v[14:17], v[102:105], v[218:221], v[14:17]
	v_mfma_f32_16x16x32_bf16 v[10:13], v[110:113], v[218:221], v[10:13]
	v_mfma_f32_16x16x32_bf16 v[54:57], v[164:167], v[190:193], v[54:57]
	v_mfma_f32_16x16x32_bf16 v[50:53], v[182:185], v[190:193], v[50:53]
	v_mfma_f32_16x16x32_bf16 v[38:41], v[164:167], v[198:201], v[38:41]
	v_mfma_f32_16x16x32_bf16 v[34:37], v[182:185], v[198:201], v[34:37]
	v_mfma_f32_16x16x32_bf16 v[22:25], v[164:167], v[206:209], v[22:25]
	v_mfma_f32_16x16x32_bf16 v[18:21], v[182:185], v[206:209], v[18:21]
	v_mfma_f32_16x16x32_bf16 v[6:9], v[164:167], v[214:217], v[6:9]
	v_mfma_f32_16x16x32_bf16 v[2:5], v[182:185], v[214:217], v[2:5]
	v_mfma_f32_16x16x32_bf16 v[54:57], v[168:171], v[194:197], v[54:57]
	v_mfma_f32_16x16x32_bf16 v[50:53], v[186:189], v[194:197], v[50:53]
	v_mfma_f32_16x16x32_bf16 v[38:41], v[168:171], v[202:205], v[38:41]
	v_mfma_f32_16x16x32_bf16 v[34:37], v[186:189], v[202:205], v[34:37]
	v_mfma_f32_16x16x32_bf16 v[22:25], v[168:171], v[210:213], v[22:25]
	v_mfma_f32_16x16x32_bf16 v[18:21], v[186:189], v[210:213], v[18:21]
	v_mfma_f32_16x16x32_bf16 v[6:9], v[168:171], v[218:221], v[6:9]
	v_mfma_f32_16x16x32_bf16 v[2:5], v[186:189], v[218:221], v[2:5]
	s_barrier
	s_add_i32 s58, s58, 2
	s_add_u32 s26, s26, 0x100
	s_addc_u32 s27, s27, 0
	s_add_u32 s56, s56, 0x100
	s_addc_u32 s57, s57, 0
	s_cmp_gt_u32 s58, 29
	s_cbranch_scc0 .LBB0_1208
	s_and_b64 vcc, exec, s[16:17]
	s_cbranch_vccz .LBB0_1211
	s_barrier

.LBB0_1284:
	ds_read_b128 v[122:125], v173
	ds_read_b128 v[126:129], v173 offset:1024
	ds_read_b128 v[130:133], v173 offset:2048
	ds_read_b128 v[134:137], v173 offset:3072
	ds_read_b128 v[164:167], v174
	ds_read_b128 v[180:183], v174 offset:1024
	ds_read_b128 v[184:187], v174 offset:2048
	ds_read_b128 v[188:191], v174 offset:3072
	s_add_u32 s28, s26, 0x100
	s_addc_u32 s29, s27, 0
	s_cmpk_eq_i32 s60, 0x54
	s_cselect_b32 s35, s5, s29
	s_cselect_b32 s34, s4, s28
	s_cselect_b32 s31, s25, s59
	s_cselect_b32 s30, s24, s58
	v_lshl_add_u64 v[168:169], s[26:27], 0, v[156:157]
	s_add_i32 m0, s38, 0xc000
	ds_read_b128 v[192:195], v175
	ds_read_b128 v[196:199], v175 offset:1024
	ds_read_b128 v[200:203], v175 offset:2048
	ds_read_b128 v[204:207], v175 offset:3072
	ds_read_b128 v[208:211], v175 offset:4096
	ds_read_b128 v[212:215], v175 offset:5120
	ds_read_b128 v[216:219], v175 offset:6144
	ds_read_b128 v[220:223], v175 offset:7168
	global_load_lds_dwordx4 v[168:169], off
	v_lshl_add_u64 v[168:169], s[26:27], 0, v[158:159]
	s_add_i32 m0, s38, 0xe000
	s_nop 0
	global_load_lds_dwordx4 v[168:169], off
	s_waitcnt vmcnt(8)
	s_waitcnt lgkmcnt(0)
	s_barrier
	v_mfma_f32_16x16x32_bf16 v[142:145], v[122:125], v[192:195], v[142:145]
	v_mfma_f32_16x16x32_bf16 v[138:141], v[130:133], v[192:195], v[138:141]
	v_mfma_f32_16x16x32_bf16 v[110:113], v[122:125], v[200:203], v[110:113]
	v_mfma_f32_16x16x32_bf16 v[106:109], v[130:133], v[200:203], v[106:109]
	v_mfma_f32_16x16x32_bf16 v[94:97], v[122:125], v[208:211], v[94:97]
	v_mfma_f32_16x16x32_bf16 v[90:93], v[130:133], v[208:211], v[90:93]
	v_mfma_f32_16x16x32_bf16 v[78:81], v[122:125], v[216:219], v[78:81]
	v_mfma_f32_16x16x32_bf16 v[74:77], v[130:133], v[216:219], v[74:77]
	v_mfma_f32_16x16x32_bf16 v[142:145], v[126:129], v[196:199], v[142:145]
	v_mfma_f32_16x16x32_bf16 v[138:141], v[134:137], v[196:199], v[138:141]
	v_mfma_f32_16x16x32_bf16 v[110:113], v[126:129], v[204:207], v[110:113]
	v_mfma_f32_16x16x32_bf16 v[106:109], v[134:137], v[204:207], v[106:109]
	v_mfma_f32_16x16x32_bf16 v[94:97], v[126:129], v[212:215], v[94:97]
	v_mfma_f32_16x16x32_bf16 v[90:93], v[134:137], v[212:215], v[90:93]
	v_mfma_f32_16x16x32_bf16 v[78:81], v[126:129], v[220:223], v[78:81]
	v_mfma_f32_16x16x32_bf16 v[74:77], v[134:137], v[220:223], v[74:77]
	v_mfma_f32_16x16x32_bf16 v[118:121], v[164:167], v[192:195], v[118:121]
	v_mfma_f32_16x16x32_bf16 v[114:117], v[184:187], v[192:195], v[114:117]
	v_mfma_f32_16x16x32_bf16 v[102:105], v[164:167], v[200:203], v[102:105]
	v_mfma_f32_16x16x32_bf16 v[98:101], v[184:187], v[200:203], v[98:101]
	v_mfma_f32_16x16x32_bf16 v[86:89], v[164:167], v[208:211], v[86:89]
	v_mfma_f32_16x16x32_bf16 v[82:85], v[184:187], v[208:211], v[82:85]
	v_mfma_f32_16x16x32_bf16 v[70:73], v[164:167], v[216:219], v[70:73]
	v_mfma_f32_16x16x32_bf16 v[66:69], v[184:187], v[216:219], v[66:69]
	v_mfma_f32_16x16x32_bf16 v[118:121], v[180:183], v[196:199], v[118:121]
	v_mfma_f32_16x16x32_bf16 v[114:117], v[188:191], v[196:199], v[114:117]
	v_mfma_f32_16x16x32_bf16 v[102:105], v[180:183], v[204:207], v[102:105]
	v_mfma_f32_16x16x32_bf16 v[98:101], v[188:191], v[204:207], v[98:101]
	v_mfma_f32_16x16x32_bf16 v[86:89], v[180:183], v[212:215], v[86:89]
	v_mfma_f32_16x16x32_bf16 v[82:85], v[188:191], v[212:215], v[82:85]
	v_mfma_f32_16x16x32_bf16 v[70:73], v[180:183], v[220:223], v[70:73]
	v_mfma_f32_16x16x32_bf16 v[66:69], v[188:191], v[220:223], v[66:69]
	s_barrier
	s_add_i32 s26, s48, s33
	v_lshl_add_u64 v[168:169], s[30:31], 0, v[152:153]
	s_mov_b32 m0, s26
	ds_read_b128 v[192:195], v175 offset:16384
	ds_read_b128 v[196:199], v175 offset:17408
	ds_read_b128 v[200:203], v175 offset:18432
	ds_read_b128 v[204:207], v175 offset:19456
	ds_read_b128 v[208:211], v175 offset:20480
	ds_read_b128 v[212:215], v175 offset:21504
	ds_read_b128 v[216:219], v175 offset:22528
	ds_read_b128 v[220:223], v175 offset:23552
	global_load_lds_dwordx4 v[168:169], off
	s_add_i32 m0, s26, 0x2000
	s_add_u32 s26, s30, 0x160000
	v_lshl_add_u64 v[176:177], s[30:31], 0, v[148:149]
	s_addc_u32 s27, s31, 0
	s_add_i32 s61, s49, s33
	global_load_lds_dwordx4 v[176:177], off
	v_lshl_add_u64 v[224:225], s[26:27], 0, v[152:153]
	s_mov_b32 m0, s61
	v_lshl_add_u64 v[226:227], s[34:35], 0, v[150:151]
	global_load_lds_dwordx4 v[224:225], off
	v_lshl_add_u64 v[224:225], s[26:27], 0, v[148:149]
	s_add_i32 m0, s61, 0x2000
	s_nop 0
	global_load_lds_dwordx4 v[224:225], off
	v_lshl_add_u64 v[224:225], s[34:35], 0, v[154:155]
	s_mov_b32 m0, s38
	s_nop 0
	global_load_lds_dwordx4 v[224:225], off
	s_mov_b32 m0, s39
	s_nop 0
	global_load_lds_dwordx4 v[226:227], off
	s_waitcnt vmcnt(8)
	s_waitcnt lgkmcnt(0)
	s_barrier
	v_mfma_f32_16x16x32_bf16 v[62:65], v[122:125], v[192:195], v[62:65]
	v_mfma_f32_16x16x32_bf16 v[58:61], v[130:133], v[192:195], v[58:61]
	v_mfma_f32_16x16x32_bf16 v[46:49], v[122:125], v[200:203], v[46:49]
	v_mfma_f32_16x16x32_bf16 v[42:45], v[130:133], v[200:203], v[42:45]
	v_mfma_f32_16x16x32_bf16 v[30:33], v[122:125], v[208:211], v[30:33]
	v_mfma_f32_16x16x32_bf16 v[26:29], v[130:133], v[208:211], v[26:29]
	v_mfma_f32_16x16x32_bf16 v[14:17], v[122:125], v[216:219], v[14:17]
	v_mfma_f32_16x16x32_bf16 v[10:13], v[130:133], v[216:219], v[10:13]
	v_mfma_f32_16x16x32_bf16 v[62:65], v[126:129], v[196:199], v[62:65]
	v_mfma_f32_16x16x32_bf16 v[58:61], v[134:137], v[196:199], v[58:61]
	v_mfma_f32_16x16x32_bf16 v[46:49], v[126:129], v[204:207], v[46:49]
	v_mfma_f32_16x16x32_bf16 v[42:45], v[134:137], v[204:207], v[42:45]
	v_mfma_f32_16x16x32_bf16 v[30:33], v[126:129], v[212:215], v[30:33]
	v_mfma_f32_16x16x32_bf16 v[26:29], v[134:137], v[212:215], v[26:29]
	v_mfma_f32_16x16x32_bf16 v[14:17], v[126:129], v[220:223], v[14:17]
	v_mfma_f32_16x16x32_bf16 v[10:13], v[134:137], v[220:223], v[10:13]
	v_mfma_f32_16x16x32_bf16 v[54:57], v[164:167], v[192:195], v[54:57]
	v_mfma_f32_16x16x32_bf16 v[50:53], v[184:187], v[192:195], v[50:53]
	v_mfma_f32_16x16x32_bf16 v[38:41], v[164:167], v[200:203], v[38:41]
	v_mfma_f32_16x16x32_bf16 v[34:37], v[184:187], v[200:203], v[34:37]
	v_mfma_f32_16x16x32_bf16 v[22:25], v[164:167], v[208:211], v[22:25]
	v_mfma_f32_16x16x32_bf16 v[18:21], v[184:187], v[208:211], v[18:21]
	v_mfma_f32_16x16x32_bf16 v[6:9], v[164:167], v[216:219], v[6:9]
	v_mfma_f32_16x16x32_bf16 v[2:5], v[184:187], v[216:219], v[2:5]
	v_mfma_f32_16x16x32_bf16 v[54:57], v[180:183], v[196:199], v[54:57]
	v_mfma_f32_16x16x32_bf16 v[50:53], v[188:191], v[196:199], v[50:53]
	v_mfma_f32_16x16x32_bf16 v[38:41], v[180:183], v[204:207], v[38:41]
	v_mfma_f32_16x16x32_bf16 v[34:37], v[188:191], v[204:207], v[34:37]
	v_mfma_f32_16x16x32_bf16 v[22:25], v[180:183], v[212:215], v[22:25]
	v_mfma_f32_16x16x32_bf16 v[18:21], v[188:191], v[212:215], v[18:21]
	v_mfma_f32_16x16x32_bf16 v[6:9], v[180:183], v[220:223], v[6:9]
	v_mfma_f32_16x16x32_bf16 v[2:5], v[188:191], v[220:223], v[2:5]
	s_barrier
	s_add_i32 s61, 0, 0x18000
	s_add_i32 s68, 0, 0x1c000
	v_add_u32_e32 v134, s61, v171
	v_add_u32_e32 v179, s68, v171
	ds_read_b128 v[122:125], v134
	ds_read_b128 v[126:129], v134 offset:1024
	ds_read_b128 v[130:133], v134 offset:2048
	ds_read_b128 v[134:137], v134 offset:3072
	ds_read_b128 v[164:167], v179
	ds_read_b128 v[180:183], v179 offset:1024
	ds_read_b128 v[184:187], v179 offset:2048
	ds_read_b128 v[188:191], v179 offset:3072
	s_add_u32 s26, s34, 0x160000
	s_addc_u32 s27, s35, 0
	s_mov_b32 m0, s40
	v_lshl_add_u64 v[228:229], s[26:27], 0, v[154:155]
	ds_read_b128 v[192:195], v175 offset:32768
	ds_read_b128 v[196:199], v175 offset:33792
	ds_read_b128 v[200:203], v175 offset:34816
	ds_read_b128 v[204:207], v175 offset:35840
	ds_read_b128 v[208:211], v175 offset:36864
	ds_read_b128 v[212:215], v175 offset:37888
	ds_read_b128 v[216:219], v175 offset:38912
	ds_read_b128 v[220:223], v175 offset:39936
	global_load_lds_dwordx4 v[228:229], off
	v_lshl_add_u64 v[228:229], s[26:27], 0, v[150:151]
	s_mov_b32 m0, s41
	s_nop 0
	global_load_lds_dwordx4 v[228:229], off
	s_waitcnt vmcnt(8)
	s_waitcnt lgkmcnt(0)
	s_barrier
	v_mfma_f32_16x16x32_bf16 v[142:145], v[122:125], v[192:195], v[142:145]
	v_mfma_f32_16x16x32_bf16 v[138:141], v[130:133], v[192:195], v[138:141]
	v_mfma_f32_16x16x32_bf16 v[110:113], v[122:125], v[200:203], v[110:113]
	v_mfma_f32_16x16x32_bf16 v[106:109], v[130:133], v[200:203], v[106:109]
	v_mfma_f32_16x16x32_bf16 v[94:97], v[122:125], v[208:211], v[94:97]
	v_mfma_f32_16x16x32_bf16 v[90:93], v[130:133], v[208:211], v[90:93]
	v_mfma_f32_16x16x32_bf16 v[78:81], v[122:125], v[216:219], v[78:81]
	v_mfma_f32_16x16x32_bf16 v[74:77], v[130:133], v[216:219], v[74:77]
	v_mfma_f32_16x16x32_bf16 v[142:145], v[126:129], v[196:199], v[142:145]
	v_mfma_f32_16x16x32_bf16 v[138:141], v[134:137], v[196:199], v[138:141]
	v_mfma_f32_16x16x32_bf16 v[110:113], v[126:129], v[204:207], v[110:113]
	v_mfma_f32_16x16x32_bf16 v[106:109], v[134:137], v[204:207], v[106:109]
	v_mfma_f32_16x16x32_bf16 v[94:97], v[126:129], v[212:215], v[94:97]
	v_mfma_f32_16x16x32_bf16 v[90:93], v[134:137], v[212:215], v[90:93]
	v_mfma_f32_16x16x32_bf16 v[78:81], v[126:129], v[220:223], v[78:81]
	v_mfma_f32_16x16x32_bf16 v[74:77], v[134:137], v[220:223], v[74:77]
	v_mfma_f32_16x16x32_bf16 v[118:121], v[164:167], v[192:195], v[118:121]
	v_mfma_f32_16x16x32_bf16 v[114:117], v[184:187], v[192:195], v[114:117]
	v_mfma_f32_16x16x32_bf16 v[102:105], v[164:167], v[200:203], v[102:105]
	v_mfma_f32_16x16x32_bf16 v[98:101], v[184:187], v[200:203], v[98:101]
	v_mfma_f32_16x16x32_bf16 v[86:89], v[164:167], v[208:211], v[86:89]
	v_mfma_f32_16x16x32_bf16 v[82:85], v[184:187], v[208:211], v[82:85]
	v_mfma_f32_16x16x32_bf16 v[70:73], v[164:167], v[216:219], v[70:73]
	v_mfma_f32_16x16x32_bf16 v[66:69], v[184:187], v[216:219], v[66:69]
	v_mfma_f32_16x16x32_bf16 v[118:121], v[180:183], v[196:199], v[118:121]
	v_mfma_f32_16x16x32_bf16 v[114:117], v[188:191], v[196:199], v[114:117]
	v_mfma_f32_16x16x32_bf16 v[102:105], v[180:183], v[204:207], v[102:105]
	v_mfma_f32_16x16x32_bf16 v[98:101], v[188:191], v[204:207], v[98:101]
	v_mfma_f32_16x16x32_bf16 v[86:89], v[180:183], v[212:215], v[86:89]
	v_mfma_f32_16x16x32_bf16 v[82:85], v[188:191], v[212:215], v[82:85]
	v_mfma_f32_16x16x32_bf16 v[70:73], v[180:183], v[220:223], v[70:73]
	v_mfma_f32_16x16x32_bf16 v[66:69], v[188:191], v[220:223], v[66:69]
	s_barrier
	s_add_i32 s26, s61, s33
	v_lshl_add_u64 v[168:169], v[168:169], 0, s[8:9]
	s_mov_b32 m0, s26
	ds_read_b128 v[192:195], v175 offset:49152
	ds_read_b128 v[196:199], v175 offset:50176
	ds_read_b128 v[200:203], v175 offset:51200
	ds_read_b128 v[204:207], v175 offset:52224
	ds_read_b128 v[208:211], v175 offset:53248
	ds_read_b128 v[212:215], v175 offset:54272
	ds_read_b128 v[216:219], v175 offset:55296
	ds_read_b128 v[220:223], v175 offset:56320
	global_load_lds_dwordx4 v[168:169], off
	s_add_i32 m0, s26, 0x2000
	s_add_u32 s26, s30, 0x160080
	v_lshl_add_u64 v[168:169], v[176:177], 0, s[8:9]
	s_addc_u32 s27, s31, 0
	s_add_i32 s30, s68, s33
	global_load_lds_dwordx4 v[168:169], off
	v_lshl_add_u64 v[168:169], s[26:27], 0, v[152:153]
	s_mov_b32 m0, s30
	s_nop 0
	global_load_lds_dwordx4 v[168:169], off
	v_lshl_add_u64 v[168:169], s[26:27], 0, v[148:149]
	s_add_i32 m0, s30, 0x2000
	s_nop 0
	global_load_lds_dwordx4 v[168:169], off
	v_lshl_add_u64 v[168:169], v[224:225], 0, s[8:9]
	s_mov_b32 m0, s43
	s_nop 0
	global_load_lds_dwordx4 v[168:169], off
	v_lshl_add_u64 v[168:169], v[226:227], 0, s[8:9]
	s_mov_b32 m0, s44
	s_nop 0
	global_load_lds_dwordx4 v[168:169], off
	s_waitcnt vmcnt(8)
	s_waitcnt lgkmcnt(0)
	s_barrier
	v_mfma_f32_16x16x32_bf16 v[62:65], v[122:125], v[192:195], v[62:65]
	v_mfma_f32_16x16x32_bf16 v[58:61], v[130:133], v[192:195], v[58:61]
	v_mfma_f32_16x16x32_bf16 v[46:49], v[122:125], v[200:203], v[46:49]
	v_mfma_f32_16x16x32_bf16 v[42:45], v[130:133], v[200:203], v[42:45]
	v_mfma_f32_16x16x32_bf16 v[30:33], v[122:125], v[208:211], v[30:33]
	v_mfma_f32_16x16x32_bf16 v[26:29], v[130:133], v[208:211], v[26:29]
	v_mfma_f32_16x16x32_bf16 v[14:17], v[122:125], v[216:219], v[14:17]
	v_mfma_f32_16x16x32_bf16 v[10:13], v[130:133], v[216:219], v[10:13]
	v_mfma_f32_16x16x32_bf16 v[62:65], v[126:129], v[196:199], v[62:65]
	v_mfma_f32_16x16x32_bf16 v[58:61], v[134:137], v[196:199], v[58:61]
	v_mfma_f32_16x16x32_bf16 v[46:49], v[126:129], v[204:207], v[46:49]
	v_mfma_f32_16x16x32_bf16 v[42:45], v[134:137], v[204:207], v[42:45]
	v_mfma_f32_16x16x32_bf16 v[30:33], v[126:129], v[212:215], v[30:33]
	v_mfma_f32_16x16x32_bf16 v[26:29], v[134:137], v[212:215], v[26:29]
	v_mfma_f32_16x16x32_bf16 v[14:17], v[126:129], v[220:223], v[14:17]
	v_mfma_f32_16x16x32_bf16 v[10:13], v[134:137], v[220:223], v[10:13]
	v_mfma_f32_16x16x32_bf16 v[54:57], v[164:167], v[192:195], v[54:57]
	v_mfma_f32_16x16x32_bf16 v[50:53], v[184:187], v[192:195], v[50:53]
	v_mfma_f32_16x16x32_bf16 v[38:41], v[164:167], v[200:203], v[38:41]
	v_mfma_f32_16x16x32_bf16 v[34:37], v[184:187], v[200:203], v[34:37]
	v_mfma_f32_16x16x32_bf16 v[22:25], v[164:167], v[208:211], v[22:25]
	v_mfma_f32_16x16x32_bf16 v[18:21], v[184:187], v[208:211], v[18:21]
	v_mfma_f32_16x16x32_bf16 v[6:9], v[164:167], v[216:219], v[6:9]
	v_mfma_f32_16x16x32_bf16 v[2:5], v[184:187], v[216:219], v[2:5]
	v_mfma_f32_16x16x32_bf16 v[54:57], v[180:183], v[196:199], v[54:57]
	v_mfma_f32_16x16x32_bf16 v[50:53], v[188:191], v[196:199], v[50:53]
	v_mfma_f32_16x16x32_bf16 v[38:41], v[180:183], v[204:207], v[38:41]
	v_mfma_f32_16x16x32_bf16 v[34:37], v[188:191], v[204:207], v[34:37]
	v_mfma_f32_16x16x32_bf16 v[22:25], v[180:183], v[212:215], v[22:25]
	v_mfma_f32_16x16x32_bf16 v[18:21], v[188:191], v[212:215], v[18:21]
	v_mfma_f32_16x16x32_bf16 v[6:9], v[180:183], v[220:223], v[6:9]
	v_mfma_f32_16x16x32_bf16 v[2:5], v[188:191], v[220:223], v[2:5]
	s_barrier
	s_add_i32 s60, s60, 2
	s_add_u32 s58, s58, 0x100
	s_addc_u32 s59, s59, 0
	s_cmpk_gt_u32 s60, 0x55
	s_mov_b64 s[26:27], s[28:29]
	s_cbranch_scc0 .LBB0_1284
	s_and_b64 vcc, exec, s[12:13]
	s_cbranch_vccz .LBB0_1287
	s_barrier
